# weight-conversion loops: 8 tile loads issued together with counted waits (was 5 serialized HBM round trips per tile); plus LN lane exchanges via permlane/DPP
# baseline (speedup 1.0000x reference)
; DI float bflo(unsigned w) { return __uint_as_float(w << 16); }
; DI float bfhi(unsigned w) { return __uint_as_float(w & 0xffff0000u); }
; template <int NR>
; DI void ln_rows(const Args& a, int l, int row0, int lane, const f32x4 (&lgv)[4], const f32x4 (&lbv)[4], const f32x4 (&gate)[4], const f32x4 (&sh)[4], const f32x4 (&sc1)[4]) {
;     ...
;     for (int k = 0; k < NR; ++k) { const int row = row0 + k; s[k] = 0.f;
;         const float* xr = row < TL ? xlat + (size_t)row * 1024 : xctx + (size_t)(row - TL) * 1024;
; #pragma unroll
;         for (int i = 0; i < 4; ++i) { const int col = 4 * lane + 256 * i;
;             const f32x4 xv = *(const f32x4*)(xr + col); const u32x2 yw = *(const u32x2*)(y + (size_t)row * 1024 + col);
;             f32x4 yv; yv[0] = bflo(yw[0]); yv[1] = bfhi(yw[0]); yv[2] = bflo(yw[1]); yv[3] = bfhi(yw[1]);
;             v[k][i] = xv * ALPHA + gate[i] * yv; s[k] += v[k][i][0] + v[k][i][1] + v[k][i][2] + v[k][i][3]; } }
.LBB0_975:
	global_load_dwordx2 v[138:139], v[124:125], off
	global_load_dwordx2 v[140:141], v[124:125], off offset:512
	global_load_dwordx2 v[142:143], v[124:125], off offset:1024
	global_load_dwordx2 v[144:145], v[124:125], off offset:1536
	global_load_dwordx4 v[76:79], v[126:127], off offset:-2048
	global_load_dwordx4 v[72:75], v[126:127], off offset:-1024
	global_load_dwordx4 v[68:71], v[126:127], off
	global_load_dwordx4 v[64:67], v[126:127], off offset:1024
	v_add_u32_e32 v81, s69, v94
	v_add_u32_e32 v80, 4, v81
	v_add_u32_e32 v103, 3, v81
	v_add_u32_e32 v82, 5, v81
	v_ashrrev_i32_e32 v81, 31, v80
	v_lshlrev_b64 v[136:137], 11, v[80:81]
	v_lshl_add_u64 v[150:151], v[90:91], 0, v[136:137]
	global_load_dwordx2 v[152:153], v[150:151], off
	v_lshlrev_b64 v[134:135], 12, v[80:81]
	v_lshl_add_u64 v[80:81], v[86:87], 0, v[134:135]
	global_load_dwordx4 v[146:149], v[80:81], off
	v_ashrrev_i32_e32 v83, 31, v82
	v_lshlrev_b64 v[132:133], 12, v[82:83]
	v_lshlrev_b64 v[130:131], 11, v[82:83]
	global_load_dwordx2 v[188:189], v[150:151], off offset:512
	global_load_dwordx4 v[156:159], v[80:81], off offset:1024
	global_load_dwordx4 v[170:173], v[80:81], off offset:2048
	s_nop 0
	global_load_dwordx4 v[80:83], v[80:81], off offset:3072
	s_nop 0
	global_load_dwordx2 v[190:191], v[150:151], off offset:1024
	global_load_dwordx2 v[192:193], v[150:151], off offset:1536
	s_movk_i32 s0, 0x7ffe
	v_mov_b32_e32 v89, s21
	v_mov_b32_e32 v95, s20
	v_lshl_add_u64 v[154:155], s[18:19], 0, v[132:133]
	v_cmp_gt_i32_e64 s[6:7], s0, v103
	v_lshl_add_u64 v[160:161], v[90:91], 0, v[130:131]
	global_load_dwordx2 v[194:195], v[160:161], off
	global_load_dwordx2 v[196:197], v[160:161], off offset:512
	v_cndmask_b32_e64 v151, v89, v155, s[6:7]
	v_cndmask_b32_e64 v150, v95, v154, s[6:7]
	v_lshl_add_u64 v[198:199], v[150:151], 0, v[180:181]
	global_load_dwordx4 v[184:187], v[198:199], off
	s_mov_b64 s[8:9], -1
	s_waitcnt vmcnt(18)
	v_lshlrev_b32_e32 v150, 16, v138
	v_and_b32_e32 v151, 0xffff0000, v138
	s_waitcnt vmcnt(17)
	v_lshlrev_b32_e32 v154, 16, v140
	v_and_b32_e32 v155, 0xffff0000, v140
	v_lshlrev_b32_e32 v138, 16, v139
	v_and_b32_e32 v139, 0xffff0000, v139
	v_lshlrev_b32_e32 v140, 16, v141
	v_and_b32_e32 v141, 0xffff0000, v141
	s_waitcnt vmcnt(16)
	v_lshlrev_b32_e32 v162, 16, v142
	v_and_b32_e32 v163, 0xffff0000, v142
	s_waitcnt vmcnt(15)
	v_lshlrev_b32_e32 v164, 16, v144
	v_and_b32_e32 v165, 0xffff0000, v144
	v_lshlrev_b32_e32 v144, 16, v145
	v_and_b32_e32 v145, 0xffff0000, v145
	v_pk_mul_f32 v[150:151], v[60:61], v[150:151]
	v_pk_mul_f32 v[154:155], v[56:57], v[154:155]
	v_pk_mul_f32 v[138:139], v[62:63], v[138:139]
	v_pk_mul_f32 v[140:141], v[58:59], v[140:141]
	v_pk_mul_f32 v[162:163], v[52:53], v[162:163]
	v_pk_mul_f32 v[200:201], v[48:49], v[164:165]
	v_pk_mul_f32 v[144:145], v[50:51], v[144:145]
	s_waitcnt vmcnt(14)
	v_pk_fma_f32 v[178:179], v[76:77], s[44:45], v[150:151] op_sel_hi:[1,0,1]
	s_waitcnt vmcnt(13)
	v_pk_fma_f32 v[174:175], v[72:73], s[44:45], v[154:155] op_sel_hi:[1,0,1]
	v_lshlrev_b32_e32 v142, 16, v143
	v_and_b32_e32 v143, 0xffff0000, v143
	v_pk_fma_f32 v[176:177], v[78:79], s[44:45], v[138:139] op_sel_hi:[1,0,1]
	v_pk_fma_f32 v[168:169], v[74:75], s[44:45], v[140:141] op_sel_hi:[1,0,1]
	s_waitcnt vmcnt(12)
	v_pk_fma_f32 v[166:167], v[68:69], s[44:45], v[162:163] op_sel_hi:[1,0,1]
	s_waitcnt vmcnt(11)
	v_pk_fma_f32 v[154:155], v[66:67], s[44:45], v[144:145] op_sel_hi:[1,0,1]
	v_pk_fma_f32 v[162:163], v[64:65], s[44:45], v[200:201] op_sel_hi:[1,0,1]
	v_mov_b32_e32 v64, v178
	v_mov_b32_e32 v65, v174
	v_mov_b32_e32 v66, v179
	v_mov_b32_e32 v67, v175
	v_pk_mul_f32 v[142:143], v[54:55], v[142:143]
	v_mov_b32_e32 v68, v176
	v_mov_b32_e32 v69, v168
	v_pk_add_f32 v[64:65], v[64:65], v[66:67]
	v_pk_fma_f32 v[164:165], v[70:71], s[44:45], v[142:143] op_sel_hi:[1,0,1]
	v_mov_b32_e32 v70, v177
	v_mov_b32_e32 v71, v169
	v_pk_add_f32 v[64:65], v[68:69], v[64:65]
	v_mov_b32_e32 v72, v166
	v_pk_add_f32 v[64:65], v[70:71], v[64:65]
	v_mov_b32_e32 v73, v162
	v_mov_b32_e32 v74, v167
	v_mov_b32_e32 v75, v163
	v_add_f32_e32 v64, 0, v64
	v_pk_add_f32 v[66:67], v[72:73], v[74:75]
	v_add_f32_e32 v72, v64, v65
	v_mov_b32_e32 v64, v164
	v_mov_b32_e32 v65, v154
	v_pk_add_f32 v[68:69], v[64:65], v[66:67]
	v_mov_b32_e32 v70, v165
	v_mov_b32_e32 v71, v155
	global_load_dwordx4 v[64:67], v[198:199], off offset:1024
	v_pk_add_f32 v[68:69], v[70:71], v[68:69]
	s_waitcnt vmcnt(11)
	v_lshlrev_b32_e32 v70, 16, v153
	v_add_f32_e32 v68, v72, v68
	v_add_f32_e32 v89, v68, v69
	v_lshlrev_b32_e32 v68, 16, v152
	v_and_b32_e32 v69, 0xffff0000, v152
	v_and_b32_e32 v71, 0xffff0000, v153
	v_pk_mul_f32 v[68:69], v[60:61], v[68:69]
	v_pk_mul_f32 v[70:71], v[62:63], v[70:71]
	s_waitcnt vmcnt(10)
	v_pk_fma_f32 v[152:153], v[146:147], s[44:45], v[68:69] op_sel_hi:[1,0,1]
	v_pk_fma_f32 v[150:151], v[148:149], s[44:45], v[70:71] op_sel_hi:[1,0,1]
	s_waitcnt vmcnt(9)
	v_lshlrev_b32_e32 v68, 16, v188
	v_and_b32_e32 v69, 0xffff0000, v188
	v_lshlrev_b32_e32 v70, 16, v189
	global_load_dwordx2 v[74:75], v[160:161], off offset:1024
	global_load_dwordx2 v[76:77], v[160:161], off offset:1536
	v_and_b32_e32 v71, 0xffff0000, v189
	v_pk_mul_f32 v[68:69], v[56:57], v[68:69]
	v_pk_mul_f32 v[70:71], v[58:59], v[70:71]
	s_waitcnt vmcnt(10)
	v_pk_fma_f32 v[156:157], v[156:157], s[44:45], v[68:69] op_sel_hi:[1,0,1]
	v_pk_fma_f32 v[140:141], v[158:159], s[44:45], v[70:71] op_sel_hi:[1,0,1]
	global_load_dwordx4 v[68:71], v[198:199], off offset:2048
	global_load_dwordx4 v[158:161], v[198:199], off offset:3072
	v_mov_b32_e32 v72, v152
	v_mov_b32_e32 v73, v156
	v_mov_b32_e32 v78, v153
	v_mov_b32_e32 v79, v157
	v_pk_add_f32 v[72:73], v[72:73], v[78:79]
	v_mov_b32_e32 v78, v150
	v_mov_b32_e32 v79, v140
	v_pk_add_f32 v[72:73], v[78:79], v[72:73]
	v_mov_b32_e32 v78, v151
	v_mov_b32_e32 v79, v141
	v_pk_add_f32 v[72:73], v[78:79], v[72:73]
	s_waitcnt vmcnt(9)
; DI float bflo(unsigned w) { return __uint_as_float(w << 16); }
; DI float bfhi(unsigned w) { return __uint_as_float(w & 0xffff0000u); }
; DI float wave_sum(float v) {
; #pragma unroll
;     for (int o = 32; o >= 1; o >>= 1) v += __shfl_xor(v, o, 64);
;     return v;
; template <int NR>
; DI void ln_rows(const Args& a, int l, int row0, int lane, const f32x4 (&lgv)[4], const f32x4 (&lbv)[4], const f32x4 (&gate)[4], const f32x4 (&sh)[4], const f32x4 (&sc1)[4]) {
;     ...
;             const f32x4 xv = *(const f32x4*)(xr + col); const u32x2 yw = *(const u32x2*)(y + (size_t)row * 1024 + col);
;             f32x4 yv; yv[0] = bflo(yw[0]); yv[1] = bfhi(yw[0]); yv[2] = bflo(yw[1]); yv[3] = bfhi(yw[1]);
;             v[k][i] = xv * ALPHA + gate[i] * yv; s[k] += v[k][i][0] + v[k][i][1] + v[k][i][2] + v[k][i][3]; } }
;     float mean[NR], rstd[NR];
; #pragma unroll
;     for (int k = 0; k < NR; ++k) mean[k] = wave_sum(s[k]) * (1.f / 1024.f);
	v_lshlrev_b32_e32 v78, 16, v191
	v_add_f32_e32 v72, 0, v72
	v_add_f32_e32 v95, v72, v73
	v_lshlrev_b32_e32 v72, 16, v190
	v_and_b32_e32 v73, 0xffff0000, v190
	v_and_b32_e32 v79, 0xffff0000, v191
	v_pk_mul_f32 v[72:73], v[52:53], v[72:73]
	v_pk_mul_f32 v[78:79], v[54:55], v[78:79]
	v_pk_fma_f32 v[148:149], v[170:171], s[44:45], v[72:73] op_sel_hi:[1,0,1]
	s_waitcnt vmcnt(8)
	v_lshlrev_b32_e32 v72, 16, v192
	v_and_b32_e32 v73, 0xffff0000, v192
	v_pk_fma_f32 v[146:147], v[172:173], s[44:45], v[78:79] op_sel_hi:[1,0,1]
	v_lshlrev_b32_e32 v78, 16, v193
	v_and_b32_e32 v79, 0xffff0000, v193
	v_pk_mul_f32 v[72:73], v[48:49], v[72:73]
	v_pk_mul_f32 v[78:79], v[50:51], v[78:79]
	v_pk_fma_f32 v[142:143], v[80:81], s[44:45], v[72:73] op_sel_hi:[1,0,1]
	v_pk_fma_f32 v[138:139], v[82:83], s[44:45], v[78:79] op_sel_hi:[1,0,1]
	v_mov_b32_e32 v72, v148
	v_mov_b32_e32 v73, v142
	v_mov_b32_e32 v78, v149
	v_mov_b32_e32 v79, v143
	v_pk_add_f32 v[72:73], v[72:73], v[78:79]
	v_mov_b32_e32 v78, v146
	v_mov_b32_e32 v79, v138
	v_pk_add_f32 v[72:73], v[78:79], v[72:73]
	v_mov_b32_e32 v78, v147
	v_mov_b32_e32 v79, v139
	v_pk_add_f32 v[72:73], v[78:79], v[72:73]
	s_waitcnt vmcnt(7)
	v_lshlrev_b32_e32 v78, 16, v195
	v_add_f32_e32 v72, v95, v72
	v_add_f32_e32 v95, v72, v73
	v_lshlrev_b32_e32 v72, 16, v194
	v_and_b32_e32 v73, 0xffff0000, v194
	v_and_b32_e32 v79, 0xffff0000, v195
	v_pk_mul_f32 v[72:73], v[60:61], v[72:73]
	v_pk_mul_f32 v[78:79], v[62:63], v[78:79]
	s_waitcnt vmcnt(5)
	v_pk_fma_f32 v[82:83], v[184:185], s[44:45], v[72:73] op_sel_hi:[1,0,1]
	v_lshlrev_b32_e32 v72, 16, v196
	v_and_b32_e32 v73, 0xffff0000, v196
	v_pk_fma_f32 v[80:81], v[186:187], s[44:45], v[78:79] op_sel_hi:[1,0,1]
	v_lshlrev_b32_e32 v78, 16, v197
	v_and_b32_e32 v79, 0xffff0000, v197
	v_pk_mul_f32 v[144:145], v[56:57], v[72:73]
	v_pk_mul_f32 v[72:73], v[58:59], v[78:79]
	s_waitcnt vmcnt(4)
	v_pk_fma_f32 v[78:79], v[64:65], s[44:45], v[144:145] op_sel_hi:[1,0,1]
	v_pk_fma_f32 v[72:73], v[66:67], s[44:45], v[72:73] op_sel_hi:[1,0,1]
	v_mov_b32_e32 v64, v82
	v_mov_b32_e32 v65, v78
	v_mov_b32_e32 v66, v83
	v_mov_b32_e32 v67, v79
	v_pk_add_f32 v[64:65], v[64:65], v[66:67]
	v_mov_b32_e32 v66, v80
	v_mov_b32_e32 v67, v72
	v_pk_add_f32 v[64:65], v[66:67], v[64:65]
	v_mov_b32_e32 v66, v81
	v_mov_b32_e32 v67, v73
	v_pk_add_f32 v[64:65], v[66:67], v[64:65]
	s_waitcnt vmcnt(3)
	v_lshlrev_b32_e32 v66, 16, v75
	v_and_b32_e32 v67, 0xffff0000, v75
	v_add_f32_e32 v64, 0, v64
	v_pk_mul_f32 v[66:67], v[54:55], v[66:67]
	v_add_f32_e32 v103, v64, v65
	v_lshlrev_b32_e32 v64, 16, v74
	v_and_b32_e32 v65, 0xffff0000, v74
	s_waitcnt vmcnt(1)
	v_pk_fma_f32 v[70:71], v[70:71], s[44:45], v[66:67] op_sel_hi:[1,0,1]
	v_lshlrev_b32_e32 v66, 16, v77
	v_and_b32_e32 v67, 0xffff0000, v77
	v_pk_mul_f32 v[64:65], v[52:53], v[64:65]
	v_pk_mul_f32 v[66:67], v[50:51], v[66:67]
	v_pk_fma_f32 v[74:75], v[68:69], s[44:45], v[64:65] op_sel_hi:[1,0,1]
	s_waitcnt vmcnt(0)
	v_pk_fma_f32 v[68:69], v[160:161], s[44:45], v[66:67] op_sel_hi:[1,0,1]
	v_mov_b32_e32 v67, v89
	v_mov_b32_e32 v212, v89
	s_mov_b32 s100, 0
	s_mov_b32 s101, -1
	v_permlane32_swap_b32_e32 v67, v212
	v_cndmask_b32_e64 v67, v212, v67, s[100:101]
	v_lshlrev_b32_e32 v64, 16, v76
	v_and_b32_e32 v65, 0xffff0000, v76
	v_pk_mul_f32 v[64:65], v[48:49], v[64:65]
	v_mov_b32_e32 v66, v75
	s_waitcnt lgkmcnt(0)
	v_add_f32_e32 v89, v89, v67
	v_mov_b32_e32 v105, v89
	v_mov_b32_e32 v212, v89
	s_mov_b32 s100, 0xffff0000
	s_mov_b32 s101, 0xffff0000
	v_permlane16_swap_b32_e32 v105, v212
	v_cndmask_b32_e64 v105, v212, v105, s[100:101]
	v_pk_fma_f32 v[76:77], v[158:159], s[44:45], v[64:65] op_sel_hi:[1,0,1]
	v_mov_b32_e32 v64, v74
	v_mov_b32_e32 v65, v76
	v_mov_b32_e32 v67, v77
	s_waitcnt lgkmcnt(0)
	v_add_f32_e32 v89, v89, v105
	s_nop 1
	v_mov_b32_dpp v105, v89 row_ror:8 row_mask:0xf bank_mask:0xf
	v_pk_add_f32 v[64:65], v[64:65], v[66:67]
	v_mov_b32_e32 v66, v70
	v_mov_b32_e32 v67, v68
	v_pk_add_f32 v[64:65], v[66:67], v[64:65]
	v_mov_b32_e32 v66, v71
	v_mov_b32_e32 v67, v69
	v_pk_add_f32 v[64:65], v[66:67], v[64:65]
	s_waitcnt lgkmcnt(0)
	v_add_f32_e32 v66, v89, v105
	s_nop 1
	v_mov_b32_dpp v67, v66 row_ror:4 row_mask:0xf bank_mask:0xf
	v_add_f32_e32 v64, v103, v64
	v_add_f32_e32 v64, v64, v65
	v_mov_b32_e32 v65, v64
	v_mov_b32_e32 v212, v64
	s_mov_b32 s100, 0
	s_mov_b32 s101, -1
	v_permlane32_swap_b32_e32 v65, v212
	v_cndmask_b32_e64 v65, v212, v65, s[100:101]
	v_mov_b32_e32 v89, v95
	v_mov_b32_e32 v212, v95
	s_mov_b32 s100, 0
	s_mov_b32 s101, -1
	v_permlane32_swap_b32_e32 v89, v212
	v_cndmask_b32_e64 v89, v212, v89, s[100:101]
	s_waitcnt lgkmcnt(2)
	v_add_f32_e32 v66, v66, v67
	s_nop 1
	v_mov_b32_dpp v67, v66 quad_perm:[2,3,0,1] row_mask:0xf bank_mask:0xf
	s_waitcnt lgkmcnt(2)
	v_add_f32_e32 v64, v64, v65
	v_mov_b32_e32 v65, v64
	v_mov_b32_e32 v212, v64
	s_mov_b32 s100, 0xffff0000
	s_mov_b32 s101, 0xffff0000
	v_permlane16_swap_b32_e32 v65, v212
	v_cndmask_b32_e64 v65, v212, v65, s[100:101]
	s_waitcnt lgkmcnt(2)
	v_add_f32_e32 v89, v95, v89
	s_waitcnt lgkmcnt(1)
	v_add_f32_e32 v66, v66, v67
	s_nop 1
	v_mov_b32_dpp v67, v66 quad_perm:[1,0,3,2] row_mask:0xf bank_mask:0xf
	v_mov_b32_e32 v95, v89
	v_mov_b32_e32 v212, v89
	s_mov_b32 s100, 0xffff0000
	s_mov_b32 s101, 0xffff0000
	v_permlane16_swap_b32_e32 v95, v212
	v_cndmask_b32_e64 v95, v212, v95, s[100:101]
	s_waitcnt lgkmcnt(2)
	v_add_f32_e32 v64, v64, v65
	s_nop 1
	v_mov_b32_dpp v65, v64 row_ror:8 row_mask:0xf bank_mask:0xf
	s_waitcnt lgkmcnt(2)
	v_add_f32_e32 v103, v66, v67
	s_waitcnt lgkmcnt(1)
; DI float wave_sum(float v) {
; #pragma unroll
;     for (int o = 32; o >= 1; o >>= 1) v += __shfl_xor(v, o, 64);
;     return v;
; template <int NR>
; DI void ln_rows(const Args& a, int l, int row0, int lane, const f32x4 (&lgv)[4], const f32x4 (&lbv)[4], const f32x4 (&gate)[4], const f32x4 (&sh)[4], const f32x4 (&sc1)[4]) {
;     ...
;     for (int k = 0; k < NR; ++k) mean[k] = wave_sum(s[k]) * (1.f / 1024.f);
; #pragma unroll
;     for (int k = 0; k < NR; ++k) { float q = 0.f;
; #pragma unroll
;         for (int i = 0; i < 4; ++i) { v[k][i] = v[k][i] - mean[k]; q += v[k][i][0] * v[k][i][0] + v[k][i][1] * v[k][i][1] + v[k][i][2] * v[k][i][2] + v[k][i][3] * v[k][i][3]; }
;         rstd[k] = rsqrtf(wave_sum(q) * (1.f / 1024.f) + 1e-5f); }
	v_add_f32_e32 v89, v89, v95
	v_fmamk_f32 v179, v103, 0xba800000, v179
	v_fmamk_f32 v175, v103, 0xba800000, v175
	s_nop 1
	v_mov_b32_dpp v95, v89 row_ror:8 row_mask:0xf bank_mask:0xf
	v_fmac_f32_e32 v178, 0xba800000, v103
	v_fmac_f32_e32 v174, 0xba800000, v103
	v_mov_b32_e32 v66, v179
	v_mov_b32_e32 v67, v175
	s_waitcnt lgkmcnt(1)
	v_add_f32_e32 v105, v64, v65
	v_fmac_f32_e32 v176, 0xba800000, v103
	v_fmac_f32_e32 v168, 0xba800000, v103
	v_mov_b32_e32 v64, v178
	v_mov_b32_e32 v65, v174
	v_pk_mul_f32 v[66:67], v[66:67], v[66:67]
	v_fmamk_f32 v195, v103, 0xba800000, v167
	v_pk_fma_f32 v[64:65], v[64:65], v[64:65], v[66:67]
	v_mov_b32_e32 v66, v176
	v_mov_b32_e32 v67, v168
	v_fmac_f32_e32 v166, 0xba800000, v103
	v_fmamk_f32 v194, v103, 0xba800000, v163
	v_fmamk_f32 v177, v103, 0xba800000, v177
	v_pk_fma_f32 v[64:65], v[66:67], v[66:67], v[64:65]
	v_fmac_f32_e32 v164, 0xba800000, v103
	v_fmac_f32_e32 v162, 0xba800000, v103
	v_mov_b32_e32 v163, v166
	v_pk_mul_f32 v[66:67], v[194:195], v[194:195]
	v_fmamk_f32 v193, v103, 0xba800000, v169
	v_mov_b32_e32 v192, v177
	v_fmamk_f32 v188, v103, 0xba800000, v155
	v_fmac_f32_e32 v154, 0xba800000, v103
	v_pk_fma_f32 v[66:67], v[162:163], v[162:163], v[66:67]
	v_mov_b32_e32 v155, v164
	s_waitcnt lgkmcnt(0)
	v_add_f32_e32 v89, v89, v95
	v_pk_fma_f32 v[64:65], v[192:193], v[192:193], v[64:65]
	v_fmamk_f32 v189, v103, 0xba800000, v165
	v_pk_fma_f32 v[66:67], v[154:155], v[154:155], v[66:67]
	s_nop 1
	v_mov_b32_dpp v95, v89 row_ror:4 row_mask:0xf bank_mask:0xf
	s_nop 1
	v_mov_b32_dpp v107, v105 row_ror:4 row_mask:0xf bank_mask:0xf
	v_pk_fma_f32 v[66:67], v[188:189], v[188:189], v[66:67]
	v_add_f32_e32 v64, v64, v65
	v_add_f32_e32 v64, v67, v64
	v_add_f32_e32 v64, v66, v64
	v_mov_b32_e32 v65, v64
	v_mov_b32_e32 v212, v64
	s_mov_b32 s100, 0
	s_mov_b32 s101, -1
	v_permlane32_swap_b32_e32 v65, v212
	v_cndmask_b32_e64 v65, v212, v65, s[100:101]
	s_waitcnt lgkmcnt(2)
	v_add_f32_e32 v66, v89, v95
	s_waitcnt lgkmcnt(1)
	v_add_f32_e32 v89, v105, v107
	s_nop 1
	v_mov_b32_dpp v95, v89 quad_perm:[2,3,0,1] row_mask:0xf bank_mask:0xf
	s_nop 1
	v_mov_b32_dpp v67, v66 quad_perm:[2,3,0,1] row_mask:0xf bank_mask:0xf
	s_waitcnt lgkmcnt(2)
	v_add_f32_e32 v64, v64, v65
	v_mov_b32_e32 v65, v64
	v_mov_b32_e32 v212, v64
	s_mov_b32 s100, 0xffff0000
	s_mov_b32 s101, 0xffff0000
	v_permlane16_swap_b32_e32 v65, v212
	v_cndmask_b32_e64 v65, v212, v65, s[100:101]
	s_waitcnt lgkmcnt(2)
	v_add_f32_e32 v89, v89, v95
	s_waitcnt lgkmcnt(1)
	v_add_f32_e32 v66, v66, v67
	s_nop 1
	v_mov_b32_dpp v95, v89 quad_perm:[1,0,3,2] row_mask:0xf bank_mask:0xf
	s_nop 1
	v_mov_b32_dpp v67, v66 quad_perm:[1,0,3,2] row_mask:0xf bank_mask:0xf
	s_waitcnt lgkmcnt(2)
	v_add_f32_e32 v64, v64, v65
	s_nop 1
	v_mov_b32_dpp v65, v64 row_ror:8 row_mask:0xf bank_mask:0xf
	s_waitcnt lgkmcnt(2)
	v_add_f32_e32 v89, v89, v95
	s_waitcnt lgkmcnt(1)
	v_add_f32_e32 v66, v66, v67
	v_fmamk_f32 v172, v89, 0xba800000, v83
	v_fmamk_f32 v173, v89, 0xba800000, v79
	v_fmac_f32_e32 v78, 0xba800000, v89
	v_fmamk_f32 v190, v66, 0xba800000, v153
	v_fmamk_f32 v191, v66, 0xba800000, v157
	v_fmac_f32_e32 v156, 0xba800000, v66
	v_fmac_f32_e32 v82, 0xba800000, v89
	v_fmac_f32_e32 v72, 0xba800000, v89
	v_mov_b32_e32 v83, v78
	v_pk_mul_f32 v[144:145], v[172:173], v[172:173]
	s_waitcnt lgkmcnt(0)
	v_add_f32_e32 v95, v64, v65
	v_fmac_f32_e32 v152, 0xba800000, v66
	v_fmac_f32_e32 v140, 0xba800000, v66
	v_mov_b32_e32 v153, v156
	v_pk_mul_f32 v[64:65], v[190:191], v[190:191]
	v_fmamk_f32 v187, v66, 0xba800000, v149
	v_fmac_f32_e32 v148, 0xba800000, v66
	v_fmamk_f32 v186, v66, 0xba800000, v143
	v_fmamk_f32 v158, v89, 0xba800000, v81
	v_fmac_f32_e32 v80, 0xba800000, v89
	v_pk_fma_f32 v[144:145], v[82:83], v[82:83], v[144:145]
	v_mov_b32_e32 v81, v72
	v_fmamk_f32 v161, v89, 0xba800000, v75
	v_fmac_f32_e32 v74, 0xba800000, v89
	v_fmamk_f32 v160, v89, 0xba800000, v77
	v_fmamk_f32 v184, v66, 0xba800000, v151
	v_fmac_f32_e32 v150, 0xba800000, v66
	v_fmamk_f32 v185, v66, 0xba800000, v141
	v_pk_fma_f32 v[64:65], v[152:153], v[152:153], v[64:65]
	v_mov_b32_e32 v151, v140
	v_fmamk_f32 v171, v66, 0xba800000, v147
	v_fmac_f32_e32 v146, 0xba800000, v66
	v_fmamk_f32 v170, v66, 0xba800000, v139
	v_fmac_f32_e32 v138, 0xba800000, v66
	v_fmac_f32_e32 v142, 0xba800000, v66
	v_mov_b32_e32 v143, v148
	v_pk_mul_f32 v[66:67], v[186:187], v[186:187]
	v_fmamk_f32 v159, v89, 0xba800000, v73
	v_pk_fma_f32 v[144:145], v[80:81], v[80:81], v[144:145]
	v_fmac_f32_e32 v70, 0xba800000, v89
	v_fmac_f32_e32 v76, 0xba800000, v89
	v_mov_b32_e32 v77, v74
	v_pk_mul_f32 v[198:199], v[160:161], v[160:161]
	v_pk_fma_f32 v[64:65], v[150:151], v[150:151], v[64:65]
	v_pk_fma_f32 v[66:67], v[142:143], v[142:143], v[66:67]
	v_mov_b32_e32 v139, v146
	v_pk_fma_f32 v[196:197], v[158:159], v[158:159], v[144:145]
	v_fmamk_f32 v144, v89, 0xba800000, v69
	v_fmac_f32_e32 v68, 0xba800000, v89
	v_pk_fma_f32 v[198:199], v[76:77], v[76:77], v[198:199]
	v_mov_b32_e32 v69, v70
	v_pk_fma_f32 v[64:65], v[184:185], v[184:185], v[64:65]
	v_pk_fma_f32 v[66:67], v[138:139], v[138:139], v[66:67]
	v_fmamk_f32 v145, v89, 0xba800000, v71
	v_pk_fma_f32 v[198:199], v[68:69], v[68:69], v[198:199]
	v_pk_fma_f32 v[66:67], v[170:171], v[170:171], v[66:67]
	v_pk_fma_f32 v[198:199], v[144:145], v[144:145], v[198:199]
	v_mov_b32_e32 v200, v196
	v_mov_b32_e32 v201, v64
	v_mov_b32_e32 v64, v197
	v_pk_add_f32 v[64:65], v[200:201], v[64:65]
	v_mov_b32_e32 v196, v199
	v_mov_b32_e32 v197, v67
	v_pk_add_f32 v[64:65], v[196:197], v[64:65]
	v_mov_b32_e32 v199, v66
	v_pk_add_f32 v[64:65], v[198:199], v[64:65]
	v_mov_b32_e32 v67, v65
	v_mov_b32_e32 v212, v65
	s_mov_b32 s100, 0
	s_mov_b32 s101, -1
	v_permlane32_swap_b32_e32 v67, v212
	v_cndmask_b32_e64 v67, v212, v67, s[100:101]
	v_mov_b32_e32 v66, v64
	v_mov_b32_e32 v212, v64
	s_mov_b32 s100, 0
	s_mov_b32 s101, -1
	v_permlane32_swap_b32_e32 v66, v212
	v_cndmask_b32_e64 v66, v212, v66, s[100:101]
	s_nop 1
	v_mov_b32_dpp v103, v95 row_ror:4 row_mask:0xf bank_mask:0xf
	s_waitcnt lgkmcnt(1)
; DI unsigned cvt_pk_bf16(float lo, float hi) { unsigned r; asm volatile("v_cvt_pk_bf16_f32 %0, %1, %2" : "=v"(r) : "v"(lo), "v"(hi)); return r; }
; DI float wave_sum(float v) {
; #pragma unroll
;     for (int o = 32; o >= 1; o >>= 1) v += __shfl_xor(v, o, 64);
;     return v;
; template <int NR>
; DI void ln_rows(const Args& a, int l, int row0, int lane, const f32x4 (&lgv)[4], const f32x4 (&lbv)[4], const f32x4 (&gate)[4], const f32x4 (&sh)[4], const f32x4 (&sc1)[4]) {
;     ...
; #pragma unroll
;         for (int i = 0; i < 4; ++i) { v[k][i] = v[k][i] - mean[k]; q += v[k][i][0] * v[k][i][0] + v[k][i][1] * v[k][i][1] + v[k][i][2] * v[k][i][2] + v[k][i][3] * v[k][i][3]; }
;         rstd[k] = rsqrtf(wave_sum(q) * (1.f / 1024.f) + 1e-5f); }
; #pragma unroll
;     for (int k = 0; k < NR; ++k) { const int row = row0 + k;
;         float* zr = row < TL ? a.out + (size_t)row * 1024 : zc + (size_t)(row - TL) * 1024;
; #pragma unroll
;         for (int i = 0; i < 4; ++i) { const int col = 4 * lane + 256 * i;
;             const f32x4 yo = v[k][i] * rstd[k] * lgv[i] + lbv[i];
;             *(f32x4*)(zr + col) = yo;
;             if (l < 3) { const f32x4 hv = yo * sc1[i] + sh[i]; u32x2 w = {cvt_pk_bf16(hv[0], hv[1]), cvt_pk_bf16(hv[2], hv[3])}; *(u32x2*)(h + (size_t)row * 1024 + col) = w; } } }
	v_pk_add_f32 v[64:65], v[64:65], v[66:67]
	v_mov_b32_e32 v67, v65
	v_mov_b32_e32 v212, v65
	s_mov_b32 s100, 0xffff0000
	s_mov_b32 s101, 0xffff0000
	v_permlane16_swap_b32_e32 v67, v212
	v_cndmask_b32_e64 v67, v212, v67, s[100:101]
	v_mov_b32_e32 v66, v64
	v_mov_b32_e32 v212, v64
	s_mov_b32 s100, 0xffff0000
	s_mov_b32 s101, 0xffff0000
	v_permlane16_swap_b32_e32 v66, v212
	v_cndmask_b32_e64 v66, v212, v66, s[100:101]
	s_waitcnt lgkmcnt(2)
	v_add_f32_e32 v69, v95, v103
	s_nop 1
	v_mov_b32_dpp v71, v69 quad_perm:[2,3,0,1] row_mask:0xf bank_mask:0xf
	s_waitcnt lgkmcnt(1)
	v_pk_add_f32 v[64:65], v[64:65], v[66:67]
	s_nop 1
	v_mov_b32_dpp v67, v65 row_ror:8 row_mask:0xf bank_mask:0xf
	s_nop 1
	v_mov_b32_dpp v66, v64 row_ror:8 row_mask:0xf bank_mask:0xf
	s_waitcnt lgkmcnt(2)
	v_add_f32_e32 v69, v69, v71
	s_nop 1
	v_mov_b32_dpp v71, v69 quad_perm:[1,0,3,2] row_mask:0xf bank_mask:0xf
	s_waitcnt lgkmcnt(1)
	v_pk_add_f32 v[64:65], v[64:65], v[66:67]
	s_nop 1
	v_mov_b32_dpp v67, v65 row_ror:4 row_mask:0xf bank_mask:0xf
	s_nop 1
	v_mov_b32_dpp v66, v64 row_ror:4 row_mask:0xf bank_mask:0xf
	s_waitcnt lgkmcnt(2)
	v_add_f32_e32 v69, v69, v71
	v_fmamk_f32 v69, v69, 0x3a800000, v182
	v_mul_f32_e32 v71, 0x4b800000, v69
	v_cmp_gt_f32_e32 vcc, s94, v69
	s_waitcnt lgkmcnt(0)
	v_pk_add_f32 v[64:65], v[64:65], v[66:67]
	s_nop 1
	v_mov_b32_dpp v67, v65 quad_perm:[2,3,0,1] row_mask:0xf bank_mask:0xf
	s_nop 1
	v_mov_b32_dpp v66, v64 quad_perm:[2,3,0,1] row_mask:0xf bank_mask:0xf
	v_cndmask_b32_e32 v69, v69, v71, vcc
	v_rsq_f32_e32 v69, v69
	s_waitcnt lgkmcnt(0)
	v_pk_add_f32 v[196:197], v[64:65], v[66:67]
	v_mul_f32_e32 v71, 0x45800000, v69
	s_nop 1
	v_mov_b32_dpp v199, v197 quad_perm:[1,0,3,2] row_mask:0xf bank_mask:0xf
	s_nop 1
	v_mov_b32_dpp v198, v196 quad_perm:[1,0,3,2] row_mask:0xf bank_mask:0xf
	v_cndmask_b32_e32 v200, v69, v71, vcc
	v_mov_b32_e32 v201, v200
	v_pk_mul_f32 v[64:65], v[178:179], v[200:201] op_sel_hi:[1,0]
	v_pk_mul_f32 v[66:67], v[176:177], v[200:201] op_sel_hi:[1,0]
	v_cndmask_b32_e64 v69, 0, 1, s[16:17]
	v_pk_fma_f32 v[66:67], v[2:3], v[66:67], v[10:11]
	v_pk_fma_f32 v[64:65], v[0:1], v[64:65], v[8:9]
	v_cmp_ne_u32_e64 s[0:1], 1, v69
	s_andn2_b64 vcc, exec, s[16:17]
	v_pk_mul_f32 v[174:175], v[174:175], v[200:201]
	global_store_dwordx4 v[128:129], v[64:67], off offset:-3072
	s_cbranch_vccnz .LBB0_977
	s_nop 0
	v_pk_fma_f32 v[66:67], v[122:123], v[66:67], v[42:43]
	v_pk_fma_f32 v[64:65], v[120:121], v[64:65], v[40:41]
	v_mov_b32_e32 v169, v193
	v_cvt_pk_bf16_f32 v64, v64, v65
	v_cvt_pk_bf16_f32 v65, v66, v67
	v_add_co_u32_e32 v66, vcc, 0xfbc00000, v124
	s_mov_b64 s[8:9], 0
	s_nop 0
	v_addc_co_u32_e32 v67, vcc, -1, v125, vcc
	global_store_dwordx2 v[66:67], v[64:65], off
	v_mov_b32_e32 v64, v200
	v_mov_b32_e32 v65, v200
	v_pk_mul_f32 v[64:65], v[168:169], v[64:65]
	s_nop 0
	v_pk_fma_f32 v[66:67], v[6:7], v[64:65], v[14:15]
	v_pk_fma_f32 v[64:65], v[4:5], v[174:175], v[12:13]
	global_store_dwordx4 v[128:129], v[64:67], off offset:-2048
	s_nop 1
	v_pk_fma_f32 v[66:67], v[118:119], v[66:67], v[46:47]
	v_pk_fma_f32 v[64:65], v[116:117], v[64:65], v[44:45]
	s_nop 0
	v_cvt_pk_bf16_f32 v64, v64, v65
	v_cvt_pk_bf16_f32 v65, v66, v67
	v_add_co_u32_e32 v66, vcc, 0xfbc01000, v124
	s_nop 1
	v_addc_co_u32_e32 v67, vcc, -1, v125, vcc
	global_store_dwordx2 v[66:67], v[64:65], off offset:-3584

; DI float bflo(unsigned w) { return __uint_as_float(w << 16); }
; DI float bfhi(unsigned w) { return __uint_as_float(w & 0xffff0000u); }
; DI float wave_sum(float v) {
; #pragma unroll
;     for (int o = 32; o >= 1; o >>= 1) v += __shfl_xor(v, o, 64);
;     return v;
; template <int NR>
; DI void ln_rows(const Args& a, int l, int row0, int lane, const f32x4 (&lgv)[4], const f32x4 (&lbv)[4], const f32x4 (&gate)[4], const f32x4 (&sh)[4], const f32x4 (&sc1)[4]) {
;     ...
;     for (int k = 0; k < NR; ++k) { const int row = row0 + k; s[k] = 0.f;
;         const float* xr = row < TL ? xlat + (size_t)row * 1024 : xctx + (size_t)(row - TL) * 1024;
; #pragma unroll
;         for (int i = 0; i < 4; ++i) { const int col = 4 * lane + 256 * i;
;             const f32x4 xv = *(const f32x4*)(xr + col); const u32x2 yw = *(const u32x2*)(y + (size_t)row * 1024 + col);
;             f32x4 yv; yv[0] = bflo(yw[0]); yv[1] = bfhi(yw[0]); yv[2] = bflo(yw[1]); yv[3] = bfhi(yw[1]);
;             v[k][i] = xv * ALPHA + gate[i] * yv; s[k] += v[k][i][0] + v[k][i][1] + v[k][i][2] + v[k][i][3]; } }
;     float mean[NR], rstd[NR];
; #pragma unroll
;     for (int k = 0; k < NR; ++k) mean[k] = wave_sum(s[k]) * (1.f / 1024.f);
.LBB0_999:
	v_lshlrev_b32_e32 v64, 4, v211
	v_or_b32_e32 v68, 15, v64
	s_mov_b32 s6, 0x8000
	v_add_u32_e32 v64, 0xffff800f, v64
	v_mov_b32_e32 v65, v181
	v_ashrrev_i32_e32 v69, 31, v68
	v_cmp_gt_i32_e32 vcc, s6, v68
	v_lshlrev_b64 v[64:65], 12, v[64:65]
	v_lshlrev_b64 v[66:67], 12, v[68:69]
	v_lshlrev_b64 v[68:69], 11, v[68:69]
	v_lshl_add_u64 v[70:71], s[20:21], 0, v[64:65]
	v_lshl_add_u64 v[72:73], s[18:19], 0, v[66:67]
	v_lshl_add_u64 v[76:77], v[90:91], 0, v[68:69]
	v_cndmask_b32_e32 v71, v71, v73, vcc
	v_cndmask_b32_e32 v70, v70, v72, vcc
	global_load_dwordx2 v[78:79], v[76:77], off
	v_lshl_add_u64 v[74:75], v[70:71], 0, v[180:181]
	global_load_dwordx4 v[70:73], v[74:75], off
	s_waitcnt vmcnt(1)
	v_lshlrev_b32_e32 v80, 16, v78
	v_and_b32_e32 v81, 0xffff0000, v78
	v_lshlrev_b32_e32 v78, 16, v79
	v_and_b32_e32 v79, 0xffff0000, v79
	v_pk_mul_f32 v[80:81], v[60:61], v[80:81]
	v_pk_mul_f32 v[60:61], v[62:63], v[78:79]
	s_waitcnt vmcnt(0)
	v_pk_fma_f32 v[62:63], v[70:71], s[44:45], v[80:81] op_sel_hi:[1,0,1]
	v_pk_fma_f32 v[60:61], v[72:73], s[44:45], v[60:61] op_sel_hi:[1,0,1]
	global_load_dwordx4 v[70:73], v[74:75], off offset:1024
	global_load_dwordx2 v[78:79], v[76:77], off offset:512
	s_waitcnt vmcnt(0)
	v_lshlrev_b32_e32 v80, 16, v78
	v_and_b32_e32 v81, 0xffff0000, v78
	v_lshlrev_b32_e32 v78, 16, v79
	v_and_b32_e32 v79, 0xffff0000, v79
	v_pk_mul_f32 v[80:81], v[56:57], v[80:81]
	v_pk_mul_f32 v[56:57], v[58:59], v[78:79]
	v_pk_fma_f32 v[58:59], v[70:71], s[44:45], v[80:81] op_sel_hi:[1,0,1]
	v_pk_fma_f32 v[56:57], v[72:73], s[44:45], v[56:57] op_sel_hi:[1,0,1]
	v_mov_b32_e32 v70, v62
	v_mov_b32_e32 v71, v58
	v_mov_b32_e32 v72, v63
	v_mov_b32_e32 v73, v59
	v_pk_add_f32 v[70:71], v[70:71], v[72:73]
	v_mov_b32_e32 v72, v60
	v_mov_b32_e32 v73, v56
	v_pk_add_f32 v[70:71], v[72:73], v[70:71]
	v_mov_b32_e32 v72, v61
	v_mov_b32_e32 v73, v57
	v_pk_add_f32 v[70:71], v[72:73], v[70:71]
	s_nop 0
	v_add_f32_e32 v70, 0, v70
	v_add_f32_e32 v82, v70, v71
	global_load_dwordx4 v[70:73], v[74:75], off offset:2048
	global_load_dwordx2 v[78:79], v[76:77], off offset:1024
	s_waitcnt vmcnt(0)
	v_lshlrev_b32_e32 v80, 16, v78
	v_and_b32_e32 v81, 0xffff0000, v78
	v_lshlrev_b32_e32 v78, 16, v79
	v_and_b32_e32 v79, 0xffff0000, v79
	v_pk_mul_f32 v[80:81], v[52:53], v[80:81]
	v_pk_mul_f32 v[52:53], v[54:55], v[78:79]
	v_pk_fma_f32 v[54:55], v[70:71], s[44:45], v[80:81] op_sel_hi:[1,0,1]
	v_pk_fma_f32 v[52:53], v[72:73], s[44:45], v[52:53] op_sel_hi:[1,0,1]
	global_load_dwordx4 v[72:75], v[74:75], off offset:3072
	s_nop 0
	global_load_dwordx2 v[70:71], v[76:77], off offset:1536
	s_waitcnt vmcnt(0)
	v_lshlrev_b32_e32 v76, 16, v70
	v_and_b32_e32 v77, 0xffff0000, v70
	v_lshlrev_b32_e32 v70, 16, v71
	v_and_b32_e32 v71, 0xffff0000, v71
	v_pk_mul_f32 v[48:49], v[48:49], v[76:77]
	v_pk_mul_f32 v[50:51], v[50:51], v[70:71]
	v_pk_fma_f32 v[72:73], v[72:73], s[44:45], v[48:49] op_sel_hi:[1,0,1]
	v_pk_fma_f32 v[70:71], v[74:75], s[44:45], v[50:51] op_sel_hi:[1,0,1]
	v_mov_b32_e32 v48, v54
	v_mov_b32_e32 v49, v72
	v_mov_b32_e32 v50, v55
	v_mov_b32_e32 v51, v73
	v_pk_add_f32 v[48:49], v[48:49], v[50:51]
	v_mov_b32_e32 v50, v52
	v_mov_b32_e32 v51, v70
	v_pk_add_f32 v[48:49], v[50:51], v[48:49]
	v_mov_b32_e32 v50, v53
	v_mov_b32_e32 v51, v71
	v_pk_add_f32 v[48:49], v[50:51], v[48:49]
	s_nop 0
	v_add_f32_e32 v48, v82, v48
	v_add_f32_e32 v48, v48, v49
	v_mov_b32_e32 v49, v48
	v_mov_b32_e32 v212, v48
	s_mov_b32 s100, 0
	s_mov_b32 s101, -1
	v_permlane32_swap_b32_e32 v49, v212
	v_cndmask_b32_e64 v49, v212, v49, s[100:101]
	s_waitcnt lgkmcnt(0)
	v_add_f32_e32 v48, v48, v49
	v_mov_b32_e32 v49, v48
	v_mov_b32_e32 v212, v48
	s_mov_b32 s100, 0xffff0000
	s_mov_b32 s101, 0xffff0000
	v_permlane16_swap_b32_e32 v49, v212
	v_cndmask_b32_e64 v49, v212, v49, s[100:101]
	s_waitcnt lgkmcnt(0)
	v_add_f32_e32 v48, v48, v49
	s_nop 1
	v_mov_b32_dpp v49, v48 row_ror:8 row_mask:0xf bank_mask:0xf
	s_waitcnt lgkmcnt(0)
	v_add_f32_e32 v48, v48, v49
	s_nop 1
	v_mov_b32_dpp v49, v48 row_ror:4 row_mask:0xf bank_mask:0xf
	s_waitcnt lgkmcnt(0)
	v_add_f32_e32 v48, v48, v49
	s_nop 1
	v_mov_b32_dpp v49, v48 quad_perm:[2,3,0,1] row_mask:0xf bank_mask:0xf
	s_waitcnt lgkmcnt(0)
	v_add_f32_e32 v48, v48, v49
	s_nop 1
	v_mov_b32_dpp v49, v48 quad_perm:[1,0,3,2] row_mask:0xf bank_mask:0xf
	s_waitcnt lgkmcnt(0)
; DI unsigned cvt_pk_bf16(float lo, float hi) { unsigned r; asm volatile("v_cvt_pk_bf16_f32 %0, %1, %2" : "=v"(r) : "v"(lo), "v"(hi)); return r; }
; DI float wave_sum(float v) {
; #pragma unroll
;     for (int o = 32; o >= 1; o >>= 1) v += __shfl_xor(v, o, 64);
;     return v;
; template <int NR>
; DI void ln_rows(const Args& a, int l, int row0, int lane, const f32x4 (&lgv)[4], const f32x4 (&lbv)[4], const f32x4 (&gate)[4], const f32x4 (&sh)[4], const f32x4 (&sc1)[4]) {
;     ...
;     for (int k = 0; k < NR; ++k) { float q = 0.f;
; #pragma unroll
;         for (int i = 0; i < 4; ++i) { v[k][i] = v[k][i] - mean[k]; q += v[k][i][0] * v[k][i][0] + v[k][i][1] * v[k][i][1] + v[k][i][2] * v[k][i][2] + v[k][i][3] * v[k][i][3]; }
;         rstd[k] = rsqrtf(wave_sum(q) * (1.f / 1024.f) + 1e-5f); }
; #pragma unroll
;     for (int k = 0; k < NR; ++k) { const int row = row0 + k;
;         float* zr = row < TL ? a.out + (size_t)row * 1024 : zc + (size_t)(row - TL) * 1024;
; #pragma unroll
;         for (int i = 0; i < 4; ++i) { const int col = 4 * lane + 256 * i;
;             const f32x4 yo = v[k][i] * rstd[k] * lgv[i] + lbv[i];
;             *(f32x4*)(zr + col) = yo;
;             if (l < 3) { const f32x4 hv = yo * sc1[i] + sh[i]; u32x2 w = {cvt_pk_bf16(hv[0], hv[1]), cvt_pk_bf16(hv[2], hv[3])}; *(u32x2*)(h + (size_t)row * 1024 + col) = w; } } }
	v_add_f32_e32 v75, v48, v49
	v_fmamk_f32 v63, v75, 0xba800000, v63
	v_fmamk_f32 v59, v75, 0xba800000, v59
	v_fmac_f32_e32 v62, 0xba800000, v75
	v_fmac_f32_e32 v58, 0xba800000, v75
	v_mov_b32_e32 v50, v63
	v_mov_b32_e32 v51, v59
	v_fmac_f32_e32 v60, 0xba800000, v75
	v_fmac_f32_e32 v56, 0xba800000, v75
	v_mov_b32_e32 v48, v62
	v_mov_b32_e32 v49, v58
	v_pk_mul_f32 v[50:51], v[50:51], v[50:51]
	v_fmamk_f32 v55, v75, 0xba800000, v55
	v_fmamk_f32 v73, v75, 0xba800000, v73
	v_pk_fma_f32 v[48:49], v[48:49], v[48:49], v[50:51]
	v_mov_b32_e32 v50, v60
	v_mov_b32_e32 v51, v56
	v_fmac_f32_e32 v54, 0xba800000, v75
	v_fmac_f32_e32 v72, 0xba800000, v75
	v_mov_b32_e32 v78, v73
	v_mov_b32_e32 v79, v55
	v_fmamk_f32 v61, v75, 0xba800000, v61
	v_pk_fma_f32 v[48:49], v[50:51], v[50:51], v[48:49]
	v_fmac_f32_e32 v52, 0xba800000, v75
	v_mov_b32_e32 v50, v72
	v_mov_b32_e32 v51, v54
	v_pk_mul_f32 v[78:79], v[78:79], v[78:79]
	v_fmamk_f32 v77, v75, 0xba800000, v57
	v_mov_b32_e32 v76, v61
	v_fmamk_f32 v53, v75, 0xba800000, v53
	v_fmamk_f32 v74, v75, 0xba800000, v71
	v_fmac_f32_e32 v70, 0xba800000, v75
	v_pk_fma_f32 v[50:51], v[50:51], v[50:51], v[78:79]
	v_mov_b32_e32 v71, v52
	v_pk_fma_f32 v[48:49], v[76:77], v[76:77], v[48:49]
	v_pk_fma_f32 v[50:51], v[70:71], v[70:71], v[50:51]
	v_mov_b32_e32 v75, v53
	v_pk_fma_f32 v[50:51], v[74:75], v[74:75], v[50:51]
	v_add_f32_e32 v48, v48, v49
	v_add_f32_e32 v48, v51, v48
	v_add_f32_e32 v48, v50, v48
	v_mov_b32_e32 v49, v48
	v_mov_b32_e32 v212, v48
	s_mov_b32 s100, 0
	s_mov_b32 s101, -1
	v_permlane32_swap_b32_e32 v49, v212
	v_cndmask_b32_e64 v49, v212, v49, s[100:101]
	v_lshl_add_u64 v[50:51], s[26:27], 0, v[66:67]
	s_waitcnt lgkmcnt(0)
	v_add_f32_e32 v48, v48, v49
	v_mov_b32_e32 v49, v48
	v_mov_b32_e32 v212, v48
	s_mov_b32 s100, 0xffff0000
	s_mov_b32 s101, 0xffff0000
	v_permlane16_swap_b32_e32 v49, v212
	v_cndmask_b32_e64 v49, v212, v49, s[100:101]
	s_waitcnt lgkmcnt(0)
	v_add_f32_e32 v48, v48, v49
	s_nop 1
	v_mov_b32_dpp v49, v48 row_ror:8 row_mask:0xf bank_mask:0xf
	s_waitcnt lgkmcnt(0)
	v_add_f32_e32 v48, v48, v49
	s_nop 1
	v_mov_b32_dpp v49, v48 row_ror:4 row_mask:0xf bank_mask:0xf
	s_waitcnt lgkmcnt(0)
	v_add_f32_e32 v48, v48, v49
	s_nop 1
	v_mov_b32_dpp v49, v48 quad_perm:[2,3,0,1] row_mask:0xf bank_mask:0xf
	s_waitcnt lgkmcnt(0)
	v_add_f32_e32 v48, v48, v49
	s_nop 1
	v_mov_b32_dpp v49, v48 quad_perm:[1,0,3,2] row_mask:0xf bank_mask:0xf
	s_waitcnt lgkmcnt(0)
	v_add_f32_e32 v48, v48, v49
	v_fmamk_f32 v48, v48, 0x3a800000, v182
	v_cmp_gt_f32_e64 s[6:7], s94, v48
	v_mul_f32_e32 v49, 0x4b800000, v48
	s_nop 0
	v_cndmask_b32_e64 v48, v48, v49, s[6:7]
	v_rsq_f32_e32 v48, v48
	s_nop 0
	v_mul_f32_e32 v49, 0x45800000, v48
	v_cndmask_b32_e64 v78, v48, v49, s[6:7]
	v_lshl_add_u64 v[48:49], s[84:85], 0, v[64:65]
	v_mov_b32_e32 v80, v78
	v_mov_b32_e32 v81, v78
	v_cndmask_b32_e32 v67, v49, v51, vcc
	v_cndmask_b32_e32 v66, v48, v50, vcc
	v_pk_mul_f32 v[48:49], v[62:63], v[78:79] op_sel_hi:[1,0]
	v_pk_mul_f32 v[50:51], v[60:61], v[78:79] op_sel_hi:[1,0]
	v_lshl_add_u64 v[64:65], s[90:91], 0, v[68:69]
	v_pk_fma_f32 v[50:51], v[2:3], v[50:51], v[10:11]
	v_pk_fma_f32 v[48:49], v[0:1], v[48:49], v[8:9]
	v_lshl_add_u64 v[60:61], v[66:67], 0, v[180:181]
	s_mov_b64 s[6:7], -1
	s_and_b64 vcc, exec, s[0:1]
	v_pk_mul_f32 v[58:59], v[58:59], v[80:81]
	global_store_dwordx4 v[60:61], v[48:51], off
	s_cbranch_vccnz .LBB0_1001
	v_pk_fma_f32 v[40:41], v[120:121], v[48:49], v[40:41]
	v_mov_b32_e32 v89, v181
	v_pk_fma_f32 v[42:43], v[122:123], v[50:51], v[42:43]
	v_cvt_pk_bf16_f32 v40, v40, v41
	v_lshl_add_u64 v[48:49], v[64:65], 0, v[88:89]
	v_cvt_pk_bf16_f32 v41, v42, v43
	v_mov_b32_e32 v79, v78
	v_mov_b32_e32 v57, v77
	global_store_dwordx2 v[48:49], v[40:41], off
	v_pk_mul_f32 v[40:41], v[56:57], v[78:79]
	s_mov_b64 s[6:7], 0
	v_pk_fma_f32 v[42:43], v[6:7], v[40:41], v[14:15]
	v_pk_fma_f32 v[40:41], v[4:5], v[58:59], v[12:13]
	global_store_dwordx4 v[60:61], v[40:43], off offset:1024
	s_nop 1
	v_pk_fma_f32 v[40:41], v[116:117], v[40:41], v[44:45]
	v_pk_fma_f32 v[42:43], v[118:119], v[42:43], v[46:47]
	v_cvt_pk_bf16_f32 v40, v40, v41
	s_nop 0
	v_cvt_pk_bf16_f32 v41, v42, v43
	global_store_dwordx2 v[48:49], v[40:41], off offset:512

; DI float bflo(unsigned w) { return __uint_as_float(w << 16); }
; DI float bfhi(unsigned w) { return __uint_as_float(w & 0xffff0000u); }
; DI float wave_sum(float v) {
; #pragma unroll
;     for (int o = 32; o >= 1; o >>= 1) v += __shfl_xor(v, o, 64);
;     return v;
; template <int NR>
; DI void ln_rows(const Args& a, int l, int row0, int lane, const f32x4 (&lgv)[4], const f32x4 (&lbv)[4], const f32x4 (&gate)[4], const f32x4 (&sh)[4], const f32x4 (&sc1)[4]) {
;     ...
;     for (int k = 0; k < NR; ++k) { const int row = row0 + k; s[k] = 0.f;
;         const float* xr = row < TL ? xlat + (size_t)row * 1024 : xctx + (size_t)(row - TL) * 1024;
; #pragma unroll
;         for (int i = 0; i < 4; ++i) { const int col = 4 * lane + 256 * i;
;             const f32x4 xv = *(const f32x4*)(xr + col); const u32x2 yw = *(const u32x2*)(y + (size_t)row * 1024 + col);
;             f32x4 yv; yv[0] = bflo(yw[0]); yv[1] = bfhi(yw[0]); yv[2] = bflo(yw[1]); yv[3] = bfhi(yw[1]);
;             v[k][i] = xv * ALPHA + gate[i] * yv; s[k] += v[k][i][0] + v[k][i][1] + v[k][i][2] + v[k][i][3]; } }
;     float mean[NR], rstd[NR];
; #pragma unroll
;     for (int k = 0; k < NR; ++k) mean[k] = wave_sum(s[k]) * (1.f / 1024.f);
.LBB0_1010:
	v_add_u32_e32 v88, 0x8000, v84
	v_mov_b32_e32 v85, v181
	v_ashrrev_i32_e32 v89, 31, v88
	v_lshlrev_b64 v[90:91], 12, v[84:85]
	v_lshlrev_b64 v[92:93], 12, v[88:89]
	v_lshlrev_b64 v[100:101], 11, v[88:89]
	v_lshl_add_u64 v[86:87], s[6:7], 0, v[90:91]
	v_lshl_add_u64 v[88:89], s[84:85], 0, v[90:91]
	v_lshl_add_u64 v[90:91], s[4:5], 0, v[92:93]
	v_cmp_gt_i32_e32 vcc, 0, v84
	v_lshl_add_u64 v[102:103], v[80:81], 0, v[100:101]
	v_lshl_add_u64 v[104:105], s[26:27], 0, v[92:93]
	global_load_dwordx2 v[112:113], v[102:103], off
	global_load_dwordx2 v[114:115], v[102:103], off offset:512
	global_load_dwordx2 v[116:117], v[102:103], off offset:1024
	global_load_dwordx2 v[118:119], v[102:103], off offset:1536
	v_cndmask_b32_e32 v87, v87, v91, vcc
	v_cndmask_b32_e32 v86, v86, v90, vcc
	v_cndmask_b32_e32 v89, v89, v105, vcc
	v_cndmask_b32_e32 v88, v88, v104, vcc
	v_lshl_add_u64 v[90:91], v[86:87], 0, v[180:181]
	v_lshl_add_u64 v[92:93], v[82:83], 0, v[100:101]
	v_lshl_add_u64 v[120:121], v[88:89], 0, v[180:181]
	global_load_dwordx4 v[86:89], v[90:91], off
	global_load_dwordx4 v[100:103], v[90:91], off offset:1024
	global_load_dwordx4 v[104:107], v[90:91], off offset:2048
	global_load_dwordx4 v[108:111], v[90:91], off offset:3072
	v_add_u32_e32 v84, s45, v84
	v_cmp_lt_i32_e32 vcc, s46, v84
	s_or_b64 s[8:9], vcc, s[8:9]
	s_waitcnt vmcnt(7)
	v_lshlrev_b32_e32 v90, 16, v112
	v_and_b32_e32 v91, 0xffff0000, v112
	s_waitcnt vmcnt(6)
	v_lshlrev_b32_e32 v122, 16, v114
	v_and_b32_e32 v123, 0xffff0000, v114
	v_lshlrev_b32_e32 v112, 16, v113
	v_and_b32_e32 v113, 0xffff0000, v113
	v_lshlrev_b32_e32 v114, 16, v115
	v_and_b32_e32 v115, 0xffff0000, v115
	s_waitcnt vmcnt(5)
	v_lshlrev_b32_e32 v124, 16, v116
	v_and_b32_e32 v125, 0xffff0000, v116
	v_lshlrev_b32_e32 v116, 16, v117
	v_and_b32_e32 v117, 0xffff0000, v117
	s_waitcnt vmcnt(4)
	v_lshlrev_b32_e32 v126, 16, v118
	v_and_b32_e32 v127, 0xffff0000, v118
	v_lshlrev_b32_e32 v118, 16, v119
	v_and_b32_e32 v119, 0xffff0000, v119
	v_pk_mul_f32 v[90:91], v[32:33], v[90:91]
	v_pk_mul_f32 v[122:123], v[40:41], v[122:123]
	v_pk_mul_f32 v[112:113], v[34:35], v[112:113]
	v_pk_mul_f32 v[114:115], v[42:43], v[114:115]
	v_pk_mul_f32 v[116:117], v[50:51], v[116:117]
	v_pk_mul_f32 v[118:119], v[58:59], v[118:119]
	s_waitcnt vmcnt(3)
	v_pk_fma_f32 v[86:87], v[86:87], s[44:45], v[90:91] op_sel_hi:[1,0,1]
	s_waitcnt vmcnt(2)
	v_pk_fma_f32 v[100:101], v[100:101], s[44:45], v[122:123] op_sel_hi:[1,0,1]
	v_pk_mul_f32 v[124:125], v[48:49], v[124:125]
	v_pk_mul_f32 v[126:127], v[56:57], v[126:127]
	v_pk_fma_f32 v[88:89], v[88:89], s[44:45], v[112:113] op_sel_hi:[1,0,1]
	v_pk_fma_f32 v[90:91], v[102:103], s[44:45], v[114:115] op_sel_hi:[1,0,1]
	s_waitcnt vmcnt(1)
	v_pk_fma_f32 v[102:103], v[106:107], s[44:45], v[116:117] op_sel_hi:[1,0,1]
	s_waitcnt vmcnt(0)
	v_pk_fma_f32 v[106:107], v[110:111], s[44:45], v[118:119] op_sel_hi:[1,0,1]
	v_mov_b32_e32 v110, v86
	v_mov_b32_e32 v111, v100
	v_mov_b32_e32 v112, v87
	v_mov_b32_e32 v113, v101
	v_pk_fma_f32 v[104:105], v[104:105], s[44:45], v[124:125] op_sel_hi:[1,0,1]
	v_pk_fma_f32 v[108:109], v[108:109], s[44:45], v[126:127] op_sel_hi:[1,0,1]
	v_mov_b32_e32 v114, v88
	v_mov_b32_e32 v115, v90
	v_pk_add_f32 v[110:111], v[110:111], v[112:113]
	v_mov_b32_e32 v116, v89
	v_mov_b32_e32 v117, v91
	v_mov_b32_e32 v118, v104
	v_mov_b32_e32 v119, v108
	v_mov_b32_e32 v122, v105
	v_mov_b32_e32 v123, v109
	v_pk_add_f32 v[110:111], v[114:115], v[110:111]
	v_mov_b32_e32 v124, v102
	v_mov_b32_e32 v125, v106
	v_pk_add_f32 v[112:113], v[118:119], v[122:123]
	v_pk_add_f32 v[110:111], v[116:117], v[110:111]
	v_mov_b32_e32 v126, v103
	v_mov_b32_e32 v127, v107
	v_pk_add_f32 v[112:113], v[124:125], v[112:113]
	v_add_f32_e32 v85, 0, v110
	v_pk_add_f32 v[112:113], v[126:127], v[112:113]
	v_add_f32_e32 v85, v85, v111
	v_add_f32_e32 v85, v85, v112
	v_add_f32_e32 v85, v85, v113
	v_mov_b32_e32 v110, v85
	v_mov_b32_e32 v212, v85
	s_mov_b32 s100, 0
	s_mov_b32 s101, -1
	v_permlane32_swap_b32_e32 v110, v212
	v_cndmask_b32_e64 v110, v212, v110, s[100:101]
	s_waitcnt lgkmcnt(0)
	v_add_f32_e32 v85, v85, v110
	v_mov_b32_e32 v110, v85
	v_mov_b32_e32 v212, v85
	s_mov_b32 s100, 0xffff0000
	s_mov_b32 s101, 0xffff0000
	v_permlane16_swap_b32_e32 v110, v212
	v_cndmask_b32_e64 v110, v212, v110, s[100:101]
	s_waitcnt lgkmcnt(0)
	v_add_f32_e32 v85, v85, v110
	s_nop 1
	v_mov_b32_dpp v110, v85 row_ror:8 row_mask:0xf bank_mask:0xf
	s_waitcnt lgkmcnt(0)
	v_add_f32_e32 v85, v85, v110
	s_nop 1
	v_mov_b32_dpp v110, v85 row_ror:4 row_mask:0xf bank_mask:0xf
	s_waitcnt lgkmcnt(0)
	v_add_f32_e32 v85, v85, v110
	s_nop 1
	v_mov_b32_dpp v110, v85 quad_perm:[2,3,0,1] row_mask:0xf bank_mask:0xf
	s_waitcnt lgkmcnt(0)
	v_add_f32_e32 v85, v85, v110
	s_nop 1
	v_mov_b32_dpp v110, v85 quad_perm:[1,0,3,2] row_mask:0xf bank_mask:0xf
	s_waitcnt lgkmcnt(0)
; DI unsigned cvt_pk_bf16(float lo, float hi) { unsigned r; asm volatile("v_cvt_pk_bf16_f32 %0, %1, %2" : "=v"(r) : "v"(lo), "v"(hi)); return r; }
; template <int NR>
; DI void ln_rows(const Args& a, int l, int row0, int lane, const f32x4 (&lgv)[4], const f32x4 (&lbv)[4], const f32x4 (&gate)[4], const f32x4 (&sh)[4], const f32x4 (&sc1)[4]) {
;     ...
;     for (int k = 0; k < NR; ++k) { float q = 0.f;
; #pragma unroll
;         for (int i = 0; i < 4; ++i) { v[k][i] = v[k][i] - mean[k]; q += v[k][i][0] * v[k][i][0] + v[k][i][1] * v[k][i][1] + v[k][i][2] * v[k][i][2] + v[k][i][3] * v[k][i][3]; }
;         rstd[k] = rsqrtf(wave_sum(q) * (1.f / 1024.f) + 1e-5f); }
; #pragma unroll
;     for (int k = 0; k < NR; ++k) { const int row = row0 + k;
;         float* zr = row < TL ? a.out + (size_t)row * 1024 : zc + (size_t)(row - TL) * 1024;
; #pragma unroll
;         for (int i = 0; i < 4; ++i) { const int col = 4 * lane + 256 * i;
;             const f32x4 yo = v[k][i] * rstd[k] * lgv[i] + lbv[i];
;             *(f32x4*)(zr + col) = yo;
;             if (l < 3) { const f32x4 hv = yo * sc1[i] + sh[i]; u32x2 w = {cvt_pk_bf16(hv[0], hv[1]), cvt_pk_bf16(hv[2], hv[3])}; *(u32x2*)(h + (size_t)row * 1024 + col) = w; } } }
; DI void ln_phase(const Args& a, int l) {
;     ...
;         for (int gw = blockIdx.x * 8 + wid; gw < TC; gw += gridDim.x * 8) ln_rows<1>(a, l, TL + gw, lane, lgv, lbv, gate, sh, sc1);
	v_add_f32_e32 v85, v85, v110
	v_fmamk_f32 v87, v85, 0xba800000, v87
	v_fmamk_f32 v101, v85, 0xba800000, v101
	v_fmac_f32_e32 v86, 0xba800000, v85
	v_fmac_f32_e32 v100, 0xba800000, v85
	v_fmamk_f32 v105, v85, 0xba800000, v105
	v_fmamk_f32 v109, v85, 0xba800000, v109
	v_mov_b32_e32 v112, v87
	v_mov_b32_e32 v113, v101
	v_fmac_f32_e32 v88, 0xba800000, v85
	v_fmac_f32_e32 v90, 0xba800000, v85
	v_fmac_f32_e32 v104, 0xba800000, v85
	v_fmac_f32_e32 v108, 0xba800000, v85
	v_mov_b32_e32 v110, v86
	v_mov_b32_e32 v111, v100
	v_mov_b32_e32 v122, v109
	v_mov_b32_e32 v123, v105
	v_pk_mul_f32 v[112:113], v[112:113], v[112:113]
	v_fmamk_f32 v89, v85, 0xba800000, v89
	v_fmamk_f32 v91, v85, 0xba800000, v91
	v_fmac_f32_e32 v102, 0xba800000, v85
	v_fmac_f32_e32 v106, 0xba800000, v85
	v_mov_b32_e32 v114, v88
	v_mov_b32_e32 v115, v90
	v_mov_b32_e32 v118, v108
	v_mov_b32_e32 v119, v104
	v_pk_mul_f32 v[122:123], v[122:123], v[122:123]
	v_pk_fma_f32 v[110:111], v[110:111], v[110:111], v[112:113]
	v_fmamk_f32 v103, v85, 0xba800000, v103
	v_fmamk_f32 v107, v85, 0xba800000, v107
	v_mov_b32_e32 v116, v89
	v_mov_b32_e32 v117, v91
	v_mov_b32_e32 v124, v106
	v_mov_b32_e32 v125, v102
	v_pk_fma_f32 v[112:113], v[118:119], v[118:119], v[122:123]
	v_pk_fma_f32 v[110:111], v[114:115], v[114:115], v[110:111]
	v_mov_b32_e32 v126, v107
	v_mov_b32_e32 v127, v103
	v_pk_fma_f32 v[112:113], v[124:125], v[124:125], v[112:113]
	v_pk_fma_f32 v[110:111], v[116:117], v[116:117], v[110:111]
	v_pk_fma_f32 v[112:113], v[126:127], v[126:127], v[112:113]
	v_add_f32_e32 v85, v110, v111
	v_add_f32_e32 v85, v113, v85
	v_add_f32_e32 v85, v112, v85
	v_mov_b32_e32 v110, v85
	v_mov_b32_e32 v212, v85
	s_mov_b32 s100, 0
	s_mov_b32 s101, -1
	v_permlane32_swap_b32_e32 v110, v212
	v_cndmask_b32_e64 v110, v212, v110, s[100:101]
	s_waitcnt lgkmcnt(0)
	v_add_f32_e32 v85, v85, v110
	v_mov_b32_e32 v110, v85
	v_mov_b32_e32 v212, v85
	s_mov_b32 s100, 0xffff0000
	s_mov_b32 s101, 0xffff0000
	v_permlane16_swap_b32_e32 v110, v212
	v_cndmask_b32_e64 v110, v212, v110, s[100:101]
	s_waitcnt lgkmcnt(0)
	v_add_f32_e32 v85, v85, v110
	s_nop 1
	v_mov_b32_dpp v110, v85 row_ror:8 row_mask:0xf bank_mask:0xf
	s_waitcnt lgkmcnt(0)
	v_add_f32_e32 v85, v85, v110
	s_nop 1
	v_mov_b32_dpp v110, v85 row_ror:4 row_mask:0xf bank_mask:0xf
	s_waitcnt lgkmcnt(0)
	v_add_f32_e32 v85, v85, v110
	s_nop 1
	v_mov_b32_dpp v110, v85 quad_perm:[2,3,0,1] row_mask:0xf bank_mask:0xf
	s_waitcnt lgkmcnt(0)
	v_add_f32_e32 v85, v85, v110
	s_nop 1
	v_mov_b32_dpp v110, v85 quad_perm:[1,0,3,2] row_mask:0xf bank_mask:0xf
	s_waitcnt lgkmcnt(0)
	v_add_f32_e32 v85, v85, v110
	v_fmamk_f32 v85, v85, 0x3a800000, v182
	v_mul_f32_e32 v110, 0x4b800000, v85
	v_cmp_gt_f32_e32 vcc, s94, v85
	s_nop 1
	v_cndmask_b32_e32 v85, v85, v110, vcc
	v_rsq_f32_e32 v85, v85
	s_nop 0
	v_mul_f32_e32 v110, 0x45800000, v85
	v_cndmask_b32_e32 v110, v85, v110, vcc
	v_pk_mul_f32 v[86:87], v[86:87], v[110:111] op_sel_hi:[1,0]
	v_pk_mul_f32 v[88:89], v[88:89], v[110:111] op_sel_hi:[1,0]
	v_pk_fma_f32 v[86:87], v[0:1], v[86:87], v[8:9]
	v_pk_fma_f32 v[88:89], v[2:3], v[88:89], v[10:11]
	v_pk_mul_f32 v[100:101], v[100:101], v[110:111] op_sel_hi:[1,0]
	v_pk_mul_f32 v[90:91], v[90:91], v[110:111] op_sel_hi:[1,0]
	global_store_dwordx4 v[120:121], v[86:89], off
	v_pk_mul_f32 v[104:105], v[104:105], v[110:111] op_sel_hi:[1,0]
	v_pk_mul_f32 v[112:113], v[102:103], v[110:111] op_sel_hi:[1,0]
	v_pk_fma_f32 v[86:87], v[66:67], v[86:87], v[36:37]
	v_pk_fma_f32 v[102:103], v[6:7], v[90:91], v[14:15]
	v_pk_fma_f32 v[100:101], v[4:5], v[100:101], v[12:13]
	v_pk_fma_f32 v[88:89], v[64:65], v[88:89], v[38:39]
	v_cvt_pk_bf16_f32 v86, v86, v87
	v_pk_mul_f32 v[108:109], v[108:109], v[110:111] op_sel_hi:[1,0]
	v_cvt_pk_bf16_f32 v87, v88, v89
	v_pk_mul_f32 v[110:111], v[106:107], v[110:111] op_sel_hi:[1,0]
	v_pk_fma_f32 v[106:107], v[18:19], v[112:113], v[26:27]
	v_pk_fma_f32 v[104:105], v[16:17], v[104:105], v[24:25]
	v_pk_fma_f32 v[90:91], v[68:69], v[102:103], v[46:47]
	v_pk_fma_f32 v[112:113], v[70:71], v[100:101], v[44:45]
	global_store_dwordx2 v[92:93], v[86:87], off
	global_store_dwordx4 v[120:121], v[100:103], off offset:1024
	v_cvt_pk_bf16_f32 v86, v112, v113
	v_cvt_pk_bf16_f32 v87, v90, v91
	v_pk_fma_f32 v[110:111], v[22:23], v[110:111], v[30:31]
	v_pk_fma_f32 v[108:109], v[20:21], v[108:109], v[28:29]
	v_pk_fma_f32 v[114:115], v[72:73], v[106:107], v[54:55]
	v_pk_fma_f32 v[116:117], v[74:75], v[104:105], v[52:53]
	global_store_dwordx2 v[92:93], v[86:87], off offset:512
	global_store_dwordx4 v[120:121], v[104:107], off offset:2048
	v_cvt_pk_bf16_f32 v86, v116, v117
	v_cvt_pk_bf16_f32 v87, v114, v115
	v_pk_fma_f32 v[118:119], v[76:77], v[110:111], v[62:63]
	v_pk_fma_f32 v[122:123], v[78:79], v[108:109], v[60:61]
	global_store_dwordx2 v[92:93], v[86:87], off offset:1024
	global_store_dwordx4 v[120:121], v[108:111], off offset:3072
	v_cvt_pk_bf16_f32 v86, v122, v123
	v_cvt_pk_bf16_f32 v87, v118, v119
	global_store_dwordx2 v[92:93], v[86:87], off offset:1536
	s_andn2_b64 exec, exec, s[8:9]
	s_cbranch_execnz .LBB0_1010

; DI unsigned cvt_pk_bf16(float lo, float hi) { unsigned r; asm volatile("v_cvt_pk_bf16_f32 %0, %1, %2" : "=v"(r) : "v"(lo), "v"(hi)); return r; }
; DI void convert_wt(const float* __restrict__ W, bf16_t* __restrict__ Wt, int K, int N, float* tl) {
;     ...
;         const int k0 = (tile / ntn) * 64, n0 = (tile % ntn) * 64, tj = tid & 63, ti = tid >> 6;
; #pragma unroll
;         for (int ii = 0; ii < 8; ++ii) { const int k = ti * 8 + ii; tl[k * 65 + tj] = W[(size_t)(k0 + k) * N + n0 + tj]; }
;         __syncthreads();
;         const int n = tid >> 3, ks = (tid & 7) * 8;
;         u32x4 w;
;         w[0] = cvt_pk_bf16(tl[(ks + 0) * 65 + n], tl[(ks + 1) * 65 + n]); w[1] = cvt_pk_bf16(tl[(ks + 2) * 65 + n], tl[(ks + 3) * 65 + n]);
;         w[2] = cvt_pk_bf16(tl[(ks + 4) * 65 + n], tl[(ks + 5) * 65 + n]); w[3] = cvt_pk_bf16(tl[(ks + 6) * 65 + n], tl[(ks + 7) * 65 + n]);
;         *(u32x4*)(Wt + (size_t)(n0 + n) * K + k0 + ks) = w;
;         __syncthreads();
;     }
.LBB0_1014:
	s_mul_hi_i32 s4, s10, 0x66666667
	s_lshr_b32 s5, s4, 31
	s_ashr_i32 s4, s4, 4
	s_add_i32 s5, s4, s5
	s_lshl_b32 s4, s5, 6
	s_mulk_i32 s5, 0xf600
	s_add_i32 s6, s9, s5
	s_ashr_i32 s7, s6, 31
	v_lshl_add_u64 v[14:15], s[6:7], 2, v[0:1]
	s_waitcnt vmcnt(3)
	v_add_u32_e32 v20, s4, v3
	v_mad_i64_i32 v[20:21], s[12:13], v20, s11, v[14:15]
	global_load_dword v36, v[20:21], off
	v_add_u32_e32 v22, s4, v5
	v_mad_i64_i32 v[22:23], s[12:13], v22, s11, v[14:15]
	global_load_dword v37, v[22:23], off
	s_ashr_i32 s5, s4, 31
	s_add_i32 s10, s10, s30
	s_add_i32 s9, s9, s8
	s_cmpk_lt_i32 s10, 0x280
	v_add_u32_e32 v24, s4, v6
	v_mad_i64_i32 v[24:25], s[12:13], v24, s11, v[14:15]
	global_load_dword v38, v[24:25], off
	v_add_u32_e32 v26, s4, v7
	v_mad_i64_i32 v[26:27], s[12:13], v26, s11, v[14:15]
	global_load_dword v39, v[26:27], off
	v_add_u32_e32 v28, s4, v8
	v_mad_i64_i32 v[28:29], s[12:13], v28, s11, v[14:15]
	global_load_dword v40, v[28:29], off
	v_add_u32_e32 v30, s4, v9
	v_mad_i64_i32 v[30:31], s[12:13], v30, s11, v[14:15]
	global_load_dword v41, v[30:31], off
	v_add_u32_e32 v17, 0x400, v12
	v_add_u32_e32 v32, s4, v10
	v_mad_i64_i32 v[32:33], s[12:13], v32, s11, v[14:15]
	global_load_dword v42, v[32:33], off
	v_add_u32_e32 v18, 0x400, v4
	v_add_u32_e32 v34, s4, v11
	v_mad_i64_i32 v[34:35], s[12:13], v34, s11, v[14:15]
	global_load_dword v43, v[34:35], off
	s_waitcnt vmcnt(6)
	ds_write2_b32 v12, v36, v37 offset1:65
	s_waitcnt vmcnt(4)
	ds_write2_b32 v12, v38, v39 offset0:130 offset1:195
	s_waitcnt vmcnt(2)
	ds_write2_b32 v17, v40, v41 offset0:4 offset1:69
	s_waitcnt vmcnt(1)
	ds_write_b32 v12, v42 offset:1560
	s_waitcnt vmcnt(0)
	ds_write_b32 v13, v43
	s_waitcnt lgkmcnt(0)
	s_barrier
	ds_read2_b32 v[14:15], v4 offset1:65
	s_waitcnt lgkmcnt(0)
	v_cvt_pk_bf16_f32 v14, v14, v15
	ds_read2_b32 v[16:17], v4 offset0:130 offset1:195
	s_waitcnt lgkmcnt(0)
	v_cvt_pk_bf16_f32 v15, v16, v17
	ds_read2_b32 v[16:17], v18 offset0:4 offset1:69
	s_waitcnt lgkmcnt(0)
	v_cvt_pk_bf16_f32 v16, v16, v17
	ds_read2_b32 v[18:19], v18 offset0:134 offset1:199
	s_waitcnt lgkmcnt(0)
	v_cvt_pk_bf16_f32 v17, v18, v19
	v_add_u32_e32 v18, s6, v2
	v_ashrrev_i32_e32 v19, 31, v18
	v_lshlrev_b64 v[18:19], 11, v[18:19]
	v_lshl_add_u64 v[18:19], s[28:29], 0, v[18:19]
	v_lshl_add_u64 v[18:19], s[4:5], 1, v[18:19]
	v_lshl_add_u64 v[18:19], v[18:19], 0, v[180:181]
	global_store_dwordx4 v[18:19], v[14:17], off
	s_barrier
	s_cbranch_scc1 .LBB0_1014

; DI unsigned cvt_pk_bf16(float lo, float hi) { unsigned r; asm volatile("v_cvt_pk_bf16_f32 %0, %1, %2" : "=v"(r) : "v"(lo), "v"(hi)); return r; }
; DI void convert_wt(const float* __restrict__ W, bf16_t* __restrict__ Wt, int K, int N, float* tl) {
;     ...
;         const int k0 = (tile / ntn) * 64, n0 = (tile % ntn) * 64, tj = tid & 63, ti = tid >> 6;
; #pragma unroll
;         for (int ii = 0; ii < 8; ++ii) { const int k = ti * 8 + ii; tl[k * 65 + tj] = W[(size_t)(k0 + k) * N + n0 + tj]; }
;         __syncthreads();
;         const int n = tid >> 3, ks = (tid & 7) * 8;
;         u32x4 w;
;         w[0] = cvt_pk_bf16(tl[(ks + 0) * 65 + n], tl[(ks + 1) * 65 + n]); w[1] = cvt_pk_bf16(tl[(ks + 2) * 65 + n], tl[(ks + 3) * 65 + n]);
;         w[2] = cvt_pk_bf16(tl[(ks + 4) * 65 + n], tl[(ks + 5) * 65 + n]); w[3] = cvt_pk_bf16(tl[(ks + 6) * 65 + n], tl[(ks + 7) * 65 + n]);
;         *(u32x4*)(Wt + (size_t)(n0 + n) * K + k0 + ks) = w;
;         __syncthreads();
;     }
.LBB0_1017:
	s_ashr_i32 s4, s10, 31
	s_lshr_b32 s4, s4, 28
	s_add_i32 s4, s10, s4
	s_ashr_i32 s5, s4, 4
	s_lshl_b32 s4, s5, 6
	s_lshl_b32 s5, s5, 10
	s_sub_i32 s6, s9, s5
	s_waitcnt vmcnt(3)
	s_ashr_i32 s7, s6, 31
	v_lshl_add_u64 v[2:3], s[6:7], 2, v[0:1]
	v_add_u32_e32 v20, s4, v5
	v_ashrrev_i32_e32 v21, 31, v20
	v_lshlrev_b64 v[20:21], 12, v[20:21]
	v_lshl_add_u64 v[20:21], v[2:3], 0, v[20:21]
	global_load_dword v36, v[20:21], off
	v_add_u32_e32 v22, s4, v7
	v_ashrrev_i32_e32 v23, 31, v22
	v_lshlrev_b64 v[22:23], 12, v[22:23]
	v_lshl_add_u64 v[22:23], v[2:3], 0, v[22:23]
	global_load_dword v37, v[22:23], off
	v_add_u32_e32 v19, 0x400, v6
	s_ashr_i32 s5, s4, 31
	s_add_i32 s10, s10, s30
	s_add_i32 s9, s9, s8
	s_cmpk_gt_i32 s10, 0xff
	v_add_u32_e32 v24, s4, v8
	v_ashrrev_i32_e32 v25, 31, v24
	v_lshlrev_b64 v[24:25], 12, v[24:25]
	v_lshl_add_u64 v[24:25], v[2:3], 0, v[24:25]
	global_load_dword v38, v[24:25], off
	v_add_u32_e32 v26, s4, v9
	v_ashrrev_i32_e32 v27, 31, v26
	v_lshlrev_b64 v[26:27], 12, v[26:27]
	v_lshl_add_u64 v[26:27], v[2:3], 0, v[26:27]
	global_load_dword v39, v[26:27], off
	v_add_u32_e32 v28, s4, v10
	v_ashrrev_i32_e32 v29, 31, v28
	v_lshlrev_b64 v[28:29], 12, v[28:29]
	v_lshl_add_u64 v[28:29], v[2:3], 0, v[28:29]
	global_load_dword v40, v[28:29], off
	v_add_u32_e32 v30, s4, v11
	v_ashrrev_i32_e32 v31, 31, v30
	v_lshlrev_b64 v[30:31], 12, v[30:31]
	v_lshl_add_u64 v[30:31], v[2:3], 0, v[30:31]
	global_load_dword v41, v[30:31], off
	v_add_u32_e32 v17, 0x400, v14
	v_add_u32_e32 v32, s4, v12
	v_ashrrev_i32_e32 v33, 31, v32
	v_lshlrev_b64 v[32:33], 12, v[32:33]
	v_lshl_add_u64 v[32:33], v[2:3], 0, v[32:33]
	global_load_dword v42, v[32:33], off
	v_add_u32_e32 v34, s4, v13
	v_ashrrev_i32_e32 v35, 31, v34
	v_lshlrev_b64 v[34:35], 12, v[34:35]
	v_lshl_add_u64 v[34:35], v[2:3], 0, v[34:35]
	global_load_dword v43, v[34:35], off
	s_waitcnt vmcnt(6)
	ds_write2_b32 v14, v36, v37 offset1:65
	s_waitcnt vmcnt(4)
	ds_write2_b32 v14, v38, v39 offset0:130 offset1:195
	s_waitcnt vmcnt(2)
	ds_write2_b32 v17, v40, v41 offset0:4 offset1:69
	s_waitcnt vmcnt(1)
	ds_write_b32 v14, v42 offset:1560
	s_waitcnt vmcnt(0)
	ds_write_b32 v15, v43
	s_waitcnt lgkmcnt(0)
	s_barrier
	ds_read2_b32 v[2:3], v6 offset1:65
	s_waitcnt lgkmcnt(0)
	v_cvt_pk_bf16_f32 v16, v2, v3
	ds_read2_b32 v[2:3], v6 offset0:130 offset1:195
	s_waitcnt lgkmcnt(0)
	v_cvt_pk_bf16_f32 v17, v2, v3
	ds_read2_b32 v[2:3], v19 offset0:4 offset1:69
	s_waitcnt lgkmcnt(0)
	v_cvt_pk_bf16_f32 v18, v2, v3
	ds_read2_b32 v[2:3], v19 offset0:134 offset1:199
	s_waitcnt lgkmcnt(0)
	v_cvt_pk_bf16_f32 v19, v2, v3
	v_add_u32_e32 v2, s6, v4
	v_ashrrev_i32_e32 v3, 31, v2
	v_lshlrev_b64 v[2:3], 11, v[2:3]
	v_lshl_add_u64 v[2:3], s[54:55], 0, v[2:3]
	v_lshl_add_u64 v[2:3], s[4:5], 1, v[2:3]
	v_lshl_add_u64 v[2:3], v[2:3], 0, v[180:181]
	global_store_dwordx4 v[2:3], v[16:19], off
	s_barrier
	s_cbranch_scc0 .LBB0_1017

; DI unsigned cvt_pk_bf16(float lo, float hi) { unsigned r; asm volatile("v_cvt_pk_bf16_f32 %0, %1, %2" : "=v"(r) : "v"(lo), "v"(hi)); return r; }
; DI void convert_wt(const float* __restrict__ W, bf16_t* __restrict__ Wt, int K, int N, float* tl) {
;     ...
;         const int k0 = (tile / ntn) * 64, n0 = (tile % ntn) * 64, tj = tid & 63, ti = tid >> 6;
; #pragma unroll
;         for (int ii = 0; ii < 8; ++ii) { const int k = ti * 8 + ii; tl[k * 65 + tj] = W[(size_t)(k0 + k) * N + n0 + tj]; }
;         __syncthreads();
;         const int n = tid >> 3, ks = (tid & 7) * 8;
;         u32x4 w;
;         w[0] = cvt_pk_bf16(tl[(ks + 0) * 65 + n], tl[(ks + 1) * 65 + n]); w[1] = cvt_pk_bf16(tl[(ks + 2) * 65 + n], tl[(ks + 3) * 65 + n]);
;         w[2] = cvt_pk_bf16(tl[(ks + 4) * 65 + n], tl[(ks + 5) * 65 + n]); w[3] = cvt_pk_bf16(tl[(ks + 6) * 65 + n], tl[(ks + 7) * 65 + n]);
;         *(u32x4*)(Wt + (size_t)(n0 + n) * K + k0 + ks) = w;
;         __syncthreads();
;     }
.LBB0_1022:
	s_mul_hi_i32 s4, s10, 0x2aaaaaab
	s_lshr_b32 s5, s4, 31
	s_ashr_i32 s4, s4, 4
	s_add_i32 s5, s4, s5
	s_lshl_b32 s4, s5, 6
	s_mulk_i32 s5, 0xe800
	s_add_i32 s6, s9, s5
	s_ashr_i32 s7, s6, 31
	v_lshl_add_u64 v[14:15], s[6:7], 2, v[0:1]
	s_waitcnt vmcnt(3)
	v_add_u32_e32 v20, s4, v3
	v_mad_i64_i32 v[20:21], s[12:13], v20, s11, v[14:15]
	global_load_dword v36, v[20:21], off
	v_add_u32_e32 v22, s4, v5
	v_mad_i64_i32 v[22:23], s[12:13], v22, s11, v[14:15]
	global_load_dword v37, v[22:23], off
	s_ashr_i32 s5, s4, 31
	s_add_i32 s10, s10, s30
	s_add_i32 s9, s9, s8
	s_cmpk_lt_i32 s10, 0x600
	v_add_u32_e32 v24, s4, v6
	v_mad_i64_i32 v[24:25], s[12:13], v24, s11, v[14:15]
	global_load_dword v38, v[24:25], off
	v_add_u32_e32 v26, s4, v7
	v_mad_i64_i32 v[26:27], s[12:13], v26, s11, v[14:15]
	global_load_dword v39, v[26:27], off
	v_add_u32_e32 v28, s4, v8
	v_mad_i64_i32 v[28:29], s[12:13], v28, s11, v[14:15]
	global_load_dword v40, v[28:29], off
	v_add_u32_e32 v30, s4, v9
	v_mad_i64_i32 v[30:31], s[12:13], v30, s11, v[14:15]
	global_load_dword v41, v[30:31], off
	v_add_u32_e32 v17, 0x400, v12
	v_add_u32_e32 v32, s4, v10
	v_mad_i64_i32 v[32:33], s[12:13], v32, s11, v[14:15]
	global_load_dword v42, v[32:33], off
	v_add_u32_e32 v18, 0x400, v4
	v_add_u32_e32 v34, s4, v11
	v_mad_i64_i32 v[34:35], s[12:13], v34, s11, v[14:15]
	global_load_dword v43, v[34:35], off
	s_waitcnt vmcnt(6)
	ds_write2_b32 v12, v36, v37 offset1:65
	s_waitcnt vmcnt(4)
	ds_write2_b32 v12, v38, v39 offset0:130 offset1:195
	s_waitcnt vmcnt(2)
	ds_write2_b32 v17, v40, v41 offset0:4 offset1:69
	s_waitcnt vmcnt(1)
	ds_write_b32 v12, v42 offset:1560
	s_waitcnt vmcnt(0)
	ds_write_b32 v13, v43
	s_waitcnt lgkmcnt(0)
	s_barrier
	ds_read2_b32 v[14:15], v4 offset1:65
	s_waitcnt lgkmcnt(0)
	v_cvt_pk_bf16_f32 v14, v14, v15
	ds_read2_b32 v[16:17], v4 offset0:130 offset1:195
	s_waitcnt lgkmcnt(0)
	v_cvt_pk_bf16_f32 v15, v16, v17
	ds_read2_b32 v[16:17], v18 offset0:4 offset1:69
	s_waitcnt lgkmcnt(0)
	v_cvt_pk_bf16_f32 v16, v16, v17
	ds_read2_b32 v[18:19], v18 offset0:134 offset1:199
	s_waitcnt lgkmcnt(0)
	v_cvt_pk_bf16_f32 v17, v18, v19
	v_add_u32_e32 v18, s6, v2
	v_ashrrev_i32_e32 v19, 31, v18
	v_lshlrev_b64 v[18:19], 11, v[18:19]
	v_lshl_add_u64 v[18:19], s[28:29], 0, v[18:19]
	v_lshl_add_u64 v[18:19], s[4:5], 1, v[18:19]
	v_lshl_add_u64 v[18:19], v[18:19], 0, v[180:181]
	global_store_dwordx4 v[18:19], v[14:17], off
	s_barrier
	s_cbranch_scc1 .LBB0_1022

; DI unsigned cvt_pk_bf16(float lo, float hi) { unsigned r; asm volatile("v_cvt_pk_bf16_f32 %0, %1, %2" : "=v"(r) : "v"(lo), "v"(hi)); return r; }
; DI void convert_wt(const float* __restrict__ W, bf16_t* __restrict__ Wt, int K, int N, float* tl) {
;     ...
;         const int k0 = (tile / ntn) * 64, n0 = (tile % ntn) * 64, tj = tid & 63, ti = tid >> 6;
; #pragma unroll
;         for (int ii = 0; ii < 8; ++ii) { const int k = ti * 8 + ii; tl[k * 65 + tj] = W[(size_t)(k0 + k) * N + n0 + tj]; }
;         __syncthreads();
;         const int n = tid >> 3, ks = (tid & 7) * 8;
;         u32x4 w;
;         w[0] = cvt_pk_bf16(tl[(ks + 0) * 65 + n], tl[(ks + 1) * 65 + n]); w[1] = cvt_pk_bf16(tl[(ks + 2) * 65 + n], tl[(ks + 3) * 65 + n]);
;         w[2] = cvt_pk_bf16(tl[(ks + 4) * 65 + n], tl[(ks + 5) * 65 + n]); w[3] = cvt_pk_bf16(tl[(ks + 6) * 65 + n], tl[(ks + 7) * 65 + n]);
;         *(u32x4*)(Wt + (size_t)(n0 + n) * K + k0 + ks) = w;
;         __syncthreads();
;     }
.LBB0_1025:
	s_ashr_i32 s0, s8, 31
	s_lshr_b32 s0, s0, 28
	s_add_i32 s0, s8, s0
	s_ashr_i32 s1, s0, 4
	s_lshl_b32 s0, s1, 6
	s_lshl_b32 s1, s1, 10
	s_sub_i32 s4, s7, s1
	s_waitcnt vmcnt(3)
	s_ashr_i32 s5, s4, 31
	v_lshl_add_u64 v[2:3], s[4:5], 2, v[0:1]
	v_add_u32_e32 v20, s0, v5
	v_ashrrev_i32_e32 v21, 31, v20
	v_lshlrev_b64 v[20:21], 12, v[20:21]
	v_lshl_add_u64 v[20:21], v[2:3], 0, v[20:21]
	global_load_dword v36, v[20:21], off
	v_add_u32_e32 v22, s0, v7
	v_ashrrev_i32_e32 v23, 31, v22
	v_lshlrev_b64 v[22:23], 12, v[22:23]
	v_lshl_add_u64 v[22:23], v[2:3], 0, v[22:23]
	global_load_dword v37, v[22:23], off
	v_add_u32_e32 v19, 0x400, v6
	s_ashr_i32 s1, s0, 31
	s_add_i32 s8, s8, s30
	s_add_i32 s7, s7, s6
	s_cmpk_gt_i32 s8, 0x1ff
	v_add_u32_e32 v24, s0, v8
	v_ashrrev_i32_e32 v25, 31, v24
	v_lshlrev_b64 v[24:25], 12, v[24:25]
	v_lshl_add_u64 v[24:25], v[2:3], 0, v[24:25]
	global_load_dword v38, v[24:25], off
	v_add_u32_e32 v26, s0, v9
	v_ashrrev_i32_e32 v27, 31, v26
	v_lshlrev_b64 v[26:27], 12, v[26:27]
	v_lshl_add_u64 v[26:27], v[2:3], 0, v[26:27]
	global_load_dword v39, v[26:27], off
	v_add_u32_e32 v28, s0, v10
	v_ashrrev_i32_e32 v29, 31, v28
	v_lshlrev_b64 v[28:29], 12, v[28:29]
	v_lshl_add_u64 v[28:29], v[2:3], 0, v[28:29]
	global_load_dword v40, v[28:29], off
	v_add_u32_e32 v30, s0, v11
	v_ashrrev_i32_e32 v31, 31, v30
	v_lshlrev_b64 v[30:31], 12, v[30:31]
	v_lshl_add_u64 v[30:31], v[2:3], 0, v[30:31]
	global_load_dword v41, v[30:31], off
	v_add_u32_e32 v17, 0x400, v14
	v_add_u32_e32 v32, s0, v12
	v_ashrrev_i32_e32 v33, 31, v32
	v_lshlrev_b64 v[32:33], 12, v[32:33]
	v_lshl_add_u64 v[32:33], v[2:3], 0, v[32:33]
	global_load_dword v42, v[32:33], off
	v_add_u32_e32 v34, s0, v13
	v_ashrrev_i32_e32 v35, 31, v34
	v_lshlrev_b64 v[34:35], 12, v[34:35]
	v_lshl_add_u64 v[34:35], v[2:3], 0, v[34:35]
	global_load_dword v43, v[34:35], off
	s_waitcnt vmcnt(6)
	ds_write2_b32 v14, v36, v37 offset1:65
	s_waitcnt vmcnt(4)
	ds_write2_b32 v14, v38, v39 offset0:130 offset1:195
	s_waitcnt vmcnt(2)
	ds_write2_b32 v17, v40, v41 offset0:4 offset1:69
	s_waitcnt vmcnt(1)
	ds_write_b32 v14, v42 offset:1560
	s_waitcnt vmcnt(0)
	ds_write_b32 v15, v43
	s_waitcnt lgkmcnt(0)
	s_barrier
	ds_read2_b32 v[2:3], v6 offset1:65
	s_waitcnt lgkmcnt(0)
	v_cvt_pk_bf16_f32 v16, v2, v3
	ds_read2_b32 v[2:3], v6 offset0:130 offset1:195
	s_waitcnt lgkmcnt(0)
	v_cvt_pk_bf16_f32 v17, v2, v3
	ds_read2_b32 v[2:3], v19 offset0:4 offset1:69
	s_waitcnt lgkmcnt(0)
	v_cvt_pk_bf16_f32 v18, v2, v3
	ds_read2_b32 v[2:3], v19 offset0:134 offset1:199
	s_waitcnt lgkmcnt(0)
	v_cvt_pk_bf16_f32 v19, v2, v3
	v_add_u32_e32 v2, s4, v4
	v_ashrrev_i32_e32 v3, 31, v2
	v_lshlrev_b64 v[2:3], 12, v[2:3]
	v_lshl_add_u64 v[2:3], s[20:21], 0, v[2:3]
	v_lshl_add_u64 v[2:3], s[0:1], 1, v[2:3]
	v_lshl_add_u64 v[2:3], v[2:3], 0, v[180:181]
	global_store_dwordx4 v[2:3], v[16:19], off
	s_barrier
	s_cbranch_scc0 .LBB0_1025
